# RG-LRU scan MODE 1: forward-pass scratch packed to one 16-byte store / load per lane and step instead of eight 2-byte ones
# speedup vs baseline: 1.0034x; 1.0034x over previous
; #define LAS __attribute__((address_space(3)))
; #define LDS_WAIT() asm volatile("s_waitcnt lgkmcnt(0)" ::: "memory")
; __device__ __forceinline__ unsigned pk2(float lo, float hi) { const f32x2 v = {lo, hi}; return __builtin_bit_cast(unsigned, __builtin_convertvector(v, bf16x2_t)); }
; __device__ __forceinline__ void lru_prepass(const Args& a, int l, int lane, int tok0, int nb, LAS unsigned char* xt) {
;     ...
;     const int tb = tok0 + 16 * tg - 2;
; #pragma unroll
;     for (int i = 0; i < 19; ++i) { const int tt = tb + i; x[i] = (v4u){0u, 0u, 0u, 0u}; if (tt >= s0 && tt < s1) x[i] = *(const v4u*)(Z + (size_t)tt * ZRW + RXR + cbase); }
; #pragma unroll
;     for (int tp = 0; tp < 4; ++tp) { const f32x4* wp = (const f32x4*)(a.in[I_CW] + ((size_t)l * 4 + tp) * 512 + cbase); const f32x4 w0 = wp[0], w1 = wp[1];
;         cw[tp][0] = w0.x; cw[tp][1] = w0.y; cw[tp][2] = w0.z; cw[tp][3] = w0.w; cw[tp][4] = w1.x; cw[tp][5] = w1.y; cw[tp][6] = w1.z; cw[tp][7] = w1.w; }
;     { const f32x4* bp = (const f32x4*)(a.in[I_CB] + (size_t)l * 512 + cbase); const f32x4 b0 = bp[0], b1 = bp[1]; cbv[0] = b0.x; cbv[1] = b0.y; cbv[2] = b0.z; cbv[3] = b0.w; cbv[4] = b1.x; cbv[5] = b1.y; cbv[6] = b1.z; cbv[7] = b1.w; }
;     LDS_WAIT();
; #pragma unroll
;     for (int i = 0; i < 16; ++i) { float acc[8];
; #pragma unroll
;         for (int e = 0; e < 8; ++e) acc[e] = cbv[e];
; #pragma unroll
;         for (int tp = 0; tp < 4; ++tp) { const v4u xx = x[i + tp];
;             acc[0] += cw[tp][0] * bflo(xx.x); acc[1] += cw[tp][1] * bfhi(xx.x); acc[2] += cw[tp][2] * bflo(xx.y); acc[3] += cw[tp][3] * bfhi(xx.y);
;             acc[4] += cw[tp][4] * bflo(xx.z); acc[5] += cw[tp][5] * bfhi(xx.z); acc[6] += cw[tp][6] * bflo(xx.w); acc[7] += cw[tp][7] * bfhi(xx.w); }
;         v4u o; o.x = pk2(acc[0], acc[1]); o.y = pk2(acc[2], acc[3]); o.z = pk2(acc[4], acc[5]); o.w = pk2(acc[6], acc[7]);
;         *(LAS v4u*)(xt + (16 * tg + i) * 128 + oc * 16) = o; asm volatile("s_nop 1" ::: "memory"); }
.LBB0_713:
	s_or_b64 exec, exec, s[36:37]
	v_lshlrev_b32_e32 v190, 2, v40
	v_lshl_add_u64 v[54:55], s[46:47], 0, v[190:191]
	s_movk_i32 s4, 0x1000
	v_add_co_u32_e32 v56, vcc, s4, v54
	s_mov_b64 s[4:5], 0x1000
	global_load_dwordx4 v[58:61], v190, s[54:55]
	global_load_dwordx4 v[62:65], v190, s[46:47]
	global_load_dwordx4 v[38:41], v190, s[46:47] offset:16
	global_load_dwordx4 v[42:45], v190, s[54:55] offset:16
	global_load_dwordx4 v[70:73], v190, s[46:47] offset:2048
	global_load_dwordx4 v[46:49], v190, s[46:47] offset:2064
	v_addc_co_u32_e32 v57, vcc, 0, v55, vcc
	v_lshl_add_u64 v[50:51], v[54:55], 0, s[4:5]
	s_mov_b64 s[4:5], 0x1800
	global_load_dwordx4 v[78:81], v[56:57], off
	v_lshl_add_u64 v[54:55], v[54:55], 0, s[4:5]
	global_load_dwordx4 v[50:53], v[50:51], off offset:16
	s_nop 0
	global_load_dwordx4 v[82:85], v[56:57], off offset:2048
	s_waitcnt vmcnt(9)
	v_lshlrev_b32_e32 v162, 16, v114
	global_load_dwordx4 v[54:57], v[54:55], off offset:16
	v_and_b32_e32 v163, 0xffff0000, v114
	v_lshlrev_b32_e32 v114, 16, v115
	v_and_b32_e32 v115, 0xffff0000, v115
	v_lshlrev_b32_e32 v170, 16, v116
	v_and_b32_e32 v171, 0xffff0000, v116
	v_lshlrev_b32_e32 v116, 16, v117
	v_and_b32_e32 v117, 0xffff0000, v117
	v_lshlrev_b32_e32 v164, 16, v106
	v_and_b32_e32 v165, 0xffff0000, v106
	v_lshlrev_b32_e32 v106, 16, v107
	v_and_b32_e32 v107, 0xffff0000, v107
	v_lshlrev_b32_e32 v172, 16, v108
	v_and_b32_e32 v173, 0xffff0000, v108
	v_lshlrev_b32_e32 v178, 16, v109
	v_and_b32_e32 v179, 0xffff0000, v109
	v_lshlrev_b32_e32 v166, 16, v122
	v_and_b32_e32 v167, 0xffff0000, v122
	v_lshlrev_b32_e32 v122, 16, v123
	v_and_b32_e32 v123, 0xffff0000, v123
	v_lshlrev_b32_e32 v174, 16, v124
	v_and_b32_e32 v175, 0xffff0000, v124
	v_lshlrev_b32_e32 v124, 16, v125
	v_and_b32_e32 v125, 0xffff0000, v125
	v_lshlrev_b32_e32 v168, 16, v118
	v_and_b32_e32 v169, 0xffff0000, v118
	v_lshlrev_b32_e32 v118, 16, v119
	v_and_b32_e32 v119, 0xffff0000, v119
	v_lshlrev_b32_e32 v176, 16, v120
	v_and_b32_e32 v177, 0xffff0000, v120
	v_lshlrev_b32_e32 v120, 16, v121
	v_and_b32_e32 v121, 0xffff0000, v121
	s_waitcnt lgkmcnt(0)
	v_lshlrev_b32_e32 v180, 16, v110
	v_and_b32_e32 v181, 0xffff0000, v110
	v_lshlrev_b32_e32 v110, 16, v111
	v_and_b32_e32 v111, 0xffff0000, v111
	s_and_b32 s36, s62, 1
	s_lshl_b32 s4, s36, 5
	s_or_b32 s1, s1, s4
	v_readlane_b32 s8, v250, 28
	v_readlane_b32 s14, v250, 34
	v_readlane_b32 s15, v250, 35
	v_readlane_b32 s9, v250, 29
	v_readlane_b32 s12, v250, 32
	v_readlane_b32 s13, v250, 33
	s_ashr_i32 s4, s66, 5
	s_lshl_b32 s82, s0, 14
	s_movk_i32 s5, 0x2000
	s_mov_b32 s6, 0x7f800000
	s_mov_b32 s7, 0x33800000
	s_ashr_i32 s63, s62, 31
	s_lshl_b64 s[38:39], s[62:63], 13
	s_mov_b64 s[62:63], 0
	v_readlane_b32 s10, v250, 30
	v_readlane_b32 s11, v250, 31
	v_readlane_b32 s16, v250, 36
	v_readlane_b32 s17, v250, 37
	v_readlane_b32 s18, v250, 38
	v_readlane_b32 s19, v250, 39
	v_readlane_b32 s20, v250, 40
	v_readlane_b32 s21, v250, 41
	v_readlane_b32 s22, v250, 42
	v_readlane_b32 s23, v250, 43
	s_waitcnt vmcnt(8)
	v_pk_fma_f32 v[108:109], v[62:63], v[162:163], v[58:59]
	v_pk_fma_f32 v[114:115], v[64:65], v[114:115], v[60:61]
	s_waitcnt vmcnt(6)
	v_pk_fma_f32 v[162:163], v[38:39], v[170:171], v[42:43]
	v_pk_fma_f32 v[116:117], v[40:41], v[116:117], v[44:45]
	v_pk_fma_f32 v[182:183], v[64:65], v[106:107], v[60:61]
	s_waitcnt vmcnt(5)
	v_pk_fma_f32 v[108:109], v[70:71], v[164:165], v[108:109]
	v_pk_fma_f32 v[106:107], v[72:73], v[106:107], v[114:115]
	s_waitcnt vmcnt(4)
	v_pk_fma_f32 v[114:115], v[46:47], v[172:173], v[162:163]
	v_pk_fma_f32 v[116:117], v[48:49], v[178:179], v[116:117]
	s_waitcnt vmcnt(3)
	v_pk_fma_f32 v[108:109], v[78:79], v[166:167], v[108:109]
	v_pk_fma_f32 v[106:107], v[80:81], v[122:123], v[106:107]
	s_waitcnt vmcnt(2)
	v_pk_fma_f32 v[114:115], v[50:51], v[174:175], v[114:115]
	v_pk_fma_f32 v[116:117], v[52:53], v[124:125], v[116:117]
	v_pk_fma_f32 v[170:171], v[62:63], v[164:165], v[58:59]
	v_pk_fma_f32 v[184:185], v[38:39], v[172:173], v[42:43]
	s_waitcnt vmcnt(1)
	v_pk_fma_f32 v[108:109], v[82:83], v[168:169], v[108:109]
	v_pk_fma_f32 v[172:173], v[84:85], v[118:119], v[106:107]
	s_waitcnt vmcnt(0)
	v_pk_fma_f32 v[114:115], v[54:55], v[176:177], v[114:115]
	v_pk_fma_f32 v[116:117], v[56:57], v[120:121], v[116:117]
	v_pk_fma_f32 v[162:163], v[70:71], v[166:167], v[170:171]
	v_pk_fma_f32 v[170:171], v[46:47], v[174:175], v[184:185]
	v_cvt_pk_bf16_f32 v106, v108, v109
	v_cvt_pk_bf16_f32 v107, v172, v173
	v_cvt_pk_bf16_f32 v108, v114, v115
	v_cvt_pk_bf16_f32 v109, v116, v117
	ds_write_b128 v158, v[106:109]
	v_pk_fma_f32 v[106:107], v[50:51], v[176:177], v[170:171]
	v_lshlrev_b32_e32 v114, 16, v112
	v_and_b32_e32 v115, 0xffff0000, v112
	v_pk_fma_f32 v[108:109], v[54:55], v[114:115], v[106:107]
	v_pk_fma_f32 v[106:107], v[40:41], v[178:179], v[44:45]
	v_pk_fma_f32 v[164:165], v[72:73], v[122:123], v[182:183]
	v_pk_fma_f32 v[106:107], v[48:49], v[124:125], v[106:107]
	v_pk_fma_f32 v[162:163], v[78:79], v[168:169], v[162:163]
	v_pk_fma_f32 v[164:165], v[80:81], v[118:119], v[164:165]
	v_pk_fma_f32 v[106:107], v[52:53], v[120:121], v[106:107]
	v_lshlrev_b32_e32 v112, 16, v113
	v_and_b32_e32 v113, 0xffff0000, v113
	v_pk_fma_f32 v[162:163], v[82:83], v[180:181], v[162:163]
	v_pk_fma_f32 v[164:165], v[84:85], v[110:111], v[164:165]
	v_pk_fma_f32 v[116:117], v[56:57], v[112:113], v[106:107]
	v_cvt_pk_bf16_f32 v106, v162, v163
	v_cvt_pk_bf16_f32 v107, v164, v165
	v_cvt_pk_bf16_f32 v108, v108, v109
	v_cvt_pk_bf16_f32 v109, v116, v117
	s_nop 1
	ds_write_b128 v158, v[106:109] offset:128
	v_lshlrev_b32_e32 v108, 16, v98
	v_and_b32_e32 v109, 0xffff0000, v98
; #define LAS __attribute__((address_space(3)))
; __device__ __forceinline__ unsigned pk2(float lo, float hi) { const f32x2 v = {lo, hi}; return __builtin_bit_cast(unsigned, __builtin_convertvector(v, bf16x2_t)); }
; __device__ __forceinline__ void lru_prepass(const Args& a, int l, int lane, int tok0, int nb, LAS unsigned char* xt) {
;     ...
;     for (int i = 0; i < 16; ++i) { float acc[8];
; #pragma unroll
;         for (int e = 0; e < 8; ++e) acc[e] = cbv[e];
; #pragma unroll
;         for (int tp = 0; tp < 4; ++tp) { const v4u xx = x[i + tp];
;             acc[0] += cw[tp][0] * bflo(xx.x); acc[1] += cw[tp][1] * bfhi(xx.x); acc[2] += cw[tp][2] * bflo(xx.y); acc[3] += cw[tp][3] * bfhi(xx.y);
;             acc[4] += cw[tp][4] * bflo(xx.z); acc[5] += cw[tp][5] * bfhi(xx.z); acc[6] += cw[tp][6] * bflo(xx.w); acc[7] += cw[tp][7] * bfhi(xx.w); }
;         v4u o; o.x = pk2(acc[0], acc[1]); o.y = pk2(acc[2], acc[3]); o.z = pk2(acc[4], acc[5]); o.w = pk2(acc[6], acc[7]);
;         *(LAS v4u*)(xt + (16 * tg + i) * 128 + oc * 16) = o; asm volatile("s_nop 1" ::: "memory"); }
	v_pk_fma_f32 v[116:117], v[64:65], v[122:123], v[60:61]
	v_lshlrev_b32_e32 v122, 16, v99
	v_and_b32_e32 v123, 0xffff0000, v99
	v_pk_fma_f32 v[98:99], v[38:39], v[174:175], v[42:43]
	v_lshlrev_b32_e32 v162, 16, v100
	v_pk_fma_f32 v[98:99], v[46:47], v[176:177], v[98:99]
	v_and_b32_e32 v163, 0xffff0000, v100
	v_pk_fma_f32 v[98:99], v[50:51], v[114:115], v[98:99]
	v_pk_fma_f32 v[106:107], v[62:63], v[166:167], v[58:59]
	v_pk_fma_f32 v[164:165], v[54:55], v[162:163], v[98:99]
	v_pk_fma_f32 v[98:99], v[40:41], v[124:125], v[44:45]
	v_pk_fma_f32 v[106:107], v[70:71], v[168:169], v[106:107]
	v_pk_fma_f32 v[116:117], v[72:73], v[118:119], v[116:117]
	v_pk_fma_f32 v[98:99], v[48:49], v[120:121], v[98:99]
	v_pk_fma_f32 v[106:107], v[78:79], v[180:181], v[106:107]
	v_pk_fma_f32 v[116:117], v[80:81], v[110:111], v[116:117]
	v_pk_fma_f32 v[98:99], v[52:53], v[112:113], v[98:99]
	v_lshlrev_b32_e32 v124, 16, v101
	v_and_b32_e32 v125, 0xffff0000, v101
	v_pk_fma_f32 v[106:107], v[82:83], v[108:109], v[106:107]
	v_pk_fma_f32 v[116:117], v[84:85], v[122:123], v[116:117]
	v_pk_fma_f32 v[166:167], v[56:57], v[124:125], v[98:99]
	v_cvt_pk_bf16_f32 v98, v106, v107
	v_cvt_pk_bf16_f32 v99, v116, v117
	v_cvt_pk_bf16_f32 v100, v164, v165
	v_cvt_pk_bf16_f32 v101, v166, v167
	s_nop 1
	ds_write_b128 v158, v[98:101] offset:256
	v_pk_fma_f32 v[98:99], v[62:63], v[168:169], v[58:59]
	v_pk_fma_f32 v[100:101], v[64:65], v[118:119], v[60:61]
	v_pk_fma_f32 v[116:117], v[38:39], v[176:177], v[42:43]
	v_pk_fma_f32 v[120:121], v[40:41], v[120:121], v[44:45]
	v_pk_fma_f32 v[98:99], v[70:71], v[180:181], v[98:99]
	v_pk_fma_f32 v[100:101], v[72:73], v[110:111], v[100:101]
	v_pk_fma_f32 v[116:117], v[46:47], v[114:115], v[116:117]
	v_pk_fma_f32 v[120:121], v[48:49], v[112:113], v[120:121]
	v_pk_fma_f32 v[98:99], v[78:79], v[108:109], v[98:99]
	v_lshlrev_b32_e32 v106, 16, v102
	v_and_b32_e32 v107, 0xffff0000, v102
	v_pk_fma_f32 v[100:101], v[80:81], v[122:123], v[100:101]
	v_lshlrev_b32_e32 v102, 16, v103
	v_and_b32_e32 v103, 0xffff0000, v103
	v_pk_fma_f32 v[116:117], v[50:51], v[162:163], v[116:117]
	v_lshlrev_b32_e32 v118, 16, v104
	v_and_b32_e32 v119, 0xffff0000, v104
	v_pk_fma_f32 v[120:121], v[52:53], v[124:125], v[120:121]
	v_lshlrev_b32_e32 v104, 16, v105
	v_and_b32_e32 v105, 0xffff0000, v105
	v_pk_fma_f32 v[98:99], v[82:83], v[106:107], v[98:99]
	v_pk_fma_f32 v[100:101], v[84:85], v[102:103], v[100:101]
	v_pk_fma_f32 v[116:117], v[54:55], v[118:119], v[116:117]
	v_pk_fma_f32 v[120:121], v[56:57], v[104:105], v[120:121]
	v_cvt_pk_bf16_f32 v98, v98, v99
	v_cvt_pk_bf16_f32 v99, v100, v101
	v_cvt_pk_bf16_f32 v100, v116, v117
	v_cvt_pk_bf16_f32 v101, v120, v121
	s_nop 1
	ds_write_b128 v158, v[98:101] offset:384
	v_lshlrev_b32_e32 v100, 16, v90
	v_and_b32_e32 v101, 0xffff0000, v90
	v_lshlrev_b32_e32 v116, 16, v91
	v_and_b32_e32 v117, 0xffff0000, v91
	v_pk_fma_f32 v[90:91], v[38:39], v[114:115], v[42:43]
	v_lshlrev_b32_e32 v114, 16, v92
	v_pk_fma_f32 v[90:91], v[46:47], v[162:163], v[90:91]
	v_and_b32_e32 v115, 0xffff0000, v92
	v_pk_fma_f32 v[90:91], v[50:51], v[118:119], v[90:91]
	v_pk_fma_f32 v[98:99], v[62:63], v[180:181], v[58:59]
	v_pk_fma_f32 v[110:111], v[64:65], v[110:111], v[60:61]
	v_pk_fma_f32 v[120:121], v[54:55], v[114:115], v[90:91]
	v_pk_fma_f32 v[90:91], v[40:41], v[112:113], v[44:45]
	v_pk_fma_f32 v[98:99], v[70:71], v[108:109], v[98:99]
	v_pk_fma_f32 v[110:111], v[72:73], v[122:123], v[110:111]
	v_pk_fma_f32 v[90:91], v[48:49], v[124:125], v[90:91]
	v_pk_fma_f32 v[98:99], v[78:79], v[106:107], v[98:99]
	v_pk_fma_f32 v[110:111], v[80:81], v[102:103], v[110:111]
	v_pk_fma_f32 v[90:91], v[52:53], v[104:105], v[90:91]
	v_lshlrev_b32_e32 v112, 16, v93
	v_and_b32_e32 v113, 0xffff0000, v93
	v_pk_fma_f32 v[98:99], v[82:83], v[100:101], v[98:99]
	v_pk_fma_f32 v[110:111], v[84:85], v[116:117], v[110:111]
	v_pk_fma_f32 v[164:165], v[56:57], v[112:113], v[90:91]
	v_cvt_pk_bf16_f32 v90, v98, v99
	v_cvt_pk_bf16_f32 v91, v110, v111
	v_cvt_pk_bf16_f32 v92, v120, v121
	v_cvt_pk_bf16_f32 v93, v164, v165
	s_nop 1
	ds_write_b128 v158, v[90:93] offset:512
	v_pk_fma_f32 v[90:91], v[62:63], v[108:109], v[58:59]
	v_pk_fma_f32 v[92:93], v[64:65], v[122:123], v[60:61]
	v_pk_fma_f32 v[108:109], v[38:39], v[162:163], v[42:43]
	v_pk_fma_f32 v[120:121], v[40:41], v[124:125], v[44:45]
	v_pk_fma_f32 v[90:91], v[70:71], v[106:107], v[90:91]
	v_pk_fma_f32 v[92:93], v[72:73], v[102:103], v[92:93]
	v_pk_fma_f32 v[108:109], v[46:47], v[118:119], v[108:109]
	v_pk_fma_f32 v[120:121], v[48:49], v[104:105], v[120:121]
	v_pk_fma_f32 v[90:91], v[78:79], v[100:101], v[90:91]
	v_lshlrev_b32_e32 v98, 16, v94
	v_and_b32_e32 v99, 0xffff0000, v94
	v_pk_fma_f32 v[92:93], v[80:81], v[116:117], v[92:93]
	v_lshlrev_b32_e32 v94, 16, v95
	v_and_b32_e32 v95, 0xffff0000, v95
	v_pk_fma_f32 v[108:109], v[50:51], v[114:115], v[108:109]
	v_lshlrev_b32_e32 v110, 16, v96
	v_and_b32_e32 v111, 0xffff0000, v96
	v_pk_fma_f32 v[120:121], v[52:53], v[112:113], v[120:121]
	v_lshlrev_b32_e32 v96, 16, v97
	v_and_b32_e32 v97, 0xffff0000, v97
	v_pk_fma_f32 v[90:91], v[82:83], v[98:99], v[90:91]
	v_pk_fma_f32 v[92:93], v[84:85], v[94:95], v[92:93]
	v_pk_fma_f32 v[108:109], v[54:55], v[110:111], v[108:109]
	v_pk_fma_f32 v[120:121], v[56:57], v[96:97], v[120:121]
	v_cvt_pk_bf16_f32 v90, v90, v91
	v_cvt_pk_bf16_f32 v91, v92, v93
	v_cvt_pk_bf16_f32 v92, v108, v109
	v_cvt_pk_bf16_f32 v93, v120, v121
	s_nop 1
	ds_write_b128 v158, v[90:93] offset:640
	v_pk_fma_f32 v[90:91], v[62:63], v[106:107], v[58:59]
	v_lshlrev_b32_e32 v92, 16, v74
	v_and_b32_e32 v93, 0xffff0000, v74
	v_lshlrev_b32_e32 v106, 16, v75
	v_and_b32_e32 v107, 0xffff0000, v75
; #define LAS __attribute__((address_space(3)))
; __device__ __forceinline__ unsigned pk2(float lo, float hi) { const f32x2 v = {lo, hi}; return __builtin_bit_cast(unsigned, __builtin_convertvector(v, bf16x2_t)); }
; __device__ __forceinline__ void lru_prepass(const Args& a, int l, int lane, int tok0, int nb, LAS unsigned char* xt) {
;     ...
;     for (int i = 0; i < 16; ++i) { float acc[8];
; #pragma unroll
;         for (int e = 0; e < 8; ++e) acc[e] = cbv[e];
; #pragma unroll
;         for (int tp = 0; tp < 4; ++tp) { const v4u xx = x[i + tp];
;             acc[0] += cw[tp][0] * bflo(xx.x); acc[1] += cw[tp][1] * bfhi(xx.x); acc[2] += cw[tp][2] * bflo(xx.y); acc[3] += cw[tp][3] * bfhi(xx.y);
;             acc[4] += cw[tp][4] * bflo(xx.z); acc[5] += cw[tp][5] * bfhi(xx.z); acc[6] += cw[tp][6] * bflo(xx.w); acc[7] += cw[tp][7] * bfhi(xx.w); }
;         v4u o; o.x = pk2(acc[0], acc[1]); o.y = pk2(acc[2], acc[3]); o.z = pk2(acc[4], acc[5]); o.w = pk2(acc[6], acc[7]);
;         *(LAS v4u*)(xt + (16 * tg + i) * 128 + oc * 16) = o; asm volatile("s_nop 1" ::: "memory"); }
	v_pk_fma_f32 v[74:75], v[38:39], v[118:119], v[42:43]
	v_lshlrev_b32_e32 v108, 16, v76
	v_pk_fma_f32 v[74:75], v[46:47], v[114:115], v[74:75]
	v_and_b32_e32 v109, 0xffff0000, v76
	v_pk_fma_f32 v[74:75], v[50:51], v[110:111], v[74:75]
	v_pk_fma_f32 v[102:103], v[64:65], v[102:103], v[60:61]
	v_pk_fma_f32 v[118:119], v[54:55], v[108:109], v[74:75]
	v_pk_fma_f32 v[74:75], v[40:41], v[104:105], v[44:45]
	v_pk_fma_f32 v[90:91], v[70:71], v[100:101], v[90:91]
	v_pk_fma_f32 v[102:103], v[72:73], v[116:117], v[102:103]
	v_pk_fma_f32 v[74:75], v[48:49], v[112:113], v[74:75]
	v_pk_fma_f32 v[90:91], v[78:79], v[98:99], v[90:91]
	v_pk_fma_f32 v[102:103], v[80:81], v[94:95], v[102:103]
	v_pk_fma_f32 v[74:75], v[52:53], v[96:97], v[74:75]
	v_lshlrev_b32_e32 v104, 16, v77
	v_and_b32_e32 v105, 0xffff0000, v77
	v_pk_fma_f32 v[90:91], v[82:83], v[92:93], v[90:91]
	v_pk_fma_f32 v[102:103], v[84:85], v[106:107], v[102:103]
	v_pk_fma_f32 v[120:121], v[56:57], v[104:105], v[74:75]
	v_cvt_pk_bf16_f32 v74, v90, v91
	v_cvt_pk_bf16_f32 v75, v102, v103
	v_cvt_pk_bf16_f32 v76, v118, v119
	v_cvt_pk_bf16_f32 v77, v120, v121
	s_nop 1
	ds_write_b128 v158, v[74:77] offset:768
	v_pk_fma_f32 v[74:75], v[62:63], v[100:101], v[58:59]
	v_pk_fma_f32 v[76:77], v[64:65], v[116:117], v[60:61]
	v_pk_fma_f32 v[100:101], v[38:39], v[114:115], v[42:43]
	v_pk_fma_f32 v[112:113], v[40:41], v[112:113], v[44:45]
	v_pk_fma_f32 v[74:75], v[70:71], v[98:99], v[74:75]
	v_pk_fma_f32 v[76:77], v[72:73], v[94:95], v[76:77]
	v_pk_fma_f32 v[100:101], v[46:47], v[110:111], v[100:101]
	v_pk_fma_f32 v[112:113], v[48:49], v[96:97], v[112:113]
	v_pk_fma_f32 v[74:75], v[78:79], v[92:93], v[74:75]
	v_lshlrev_b32_e32 v90, 16, v86
	v_and_b32_e32 v91, 0xffff0000, v86
	v_pk_fma_f32 v[76:77], v[80:81], v[106:107], v[76:77]
	v_lshlrev_b32_e32 v86, 16, v87
	v_and_b32_e32 v87, 0xffff0000, v87
	v_pk_fma_f32 v[100:101], v[50:51], v[108:109], v[100:101]
	v_lshlrev_b32_e32 v102, 16, v88
	v_and_b32_e32 v103, 0xffff0000, v88
	v_pk_fma_f32 v[112:113], v[52:53], v[104:105], v[112:113]
	v_lshlrev_b32_e32 v88, 16, v89
	v_and_b32_e32 v89, 0xffff0000, v89
	v_pk_fma_f32 v[74:75], v[82:83], v[90:91], v[74:75]
	v_pk_fma_f32 v[76:77], v[84:85], v[86:87], v[76:77]
	v_pk_fma_f32 v[100:101], v[54:55], v[102:103], v[100:101]
	v_pk_fma_f32 v[112:113], v[56:57], v[88:89], v[112:113]
	v_cvt_pk_bf16_f32 v74, v74, v75
	v_cvt_pk_bf16_f32 v75, v76, v77
	v_cvt_pk_bf16_f32 v76, v100, v101
	v_cvt_pk_bf16_f32 v77, v112, v113
	s_nop 1
	ds_write_b128 v158, v[74:77] offset:896
	v_pk_fma_f32 v[74:75], v[62:63], v[98:99], v[58:59]
	v_lshlrev_b32_e32 v76, 16, v34
	v_and_b32_e32 v77, 0xffff0000, v34
	v_lshlrev_b32_e32 v98, 16, v35
	v_and_b32_e32 v99, 0xffff0000, v35
	v_pk_fma_f32 v[34:35], v[38:39], v[110:111], v[42:43]
	v_lshlrev_b32_e32 v100, 16, v36
	v_pk_fma_f32 v[34:35], v[46:47], v[108:109], v[34:35]
	v_and_b32_e32 v101, 0xffff0000, v36
	v_pk_fma_f32 v[34:35], v[50:51], v[102:103], v[34:35]
	v_pk_fma_f32 v[94:95], v[64:65], v[94:95], v[60:61]
	v_pk_fma_f32 v[110:111], v[54:55], v[100:101], v[34:35]
	v_pk_fma_f32 v[34:35], v[40:41], v[96:97], v[44:45]
	v_pk_fma_f32 v[74:75], v[70:71], v[92:93], v[74:75]
	v_pk_fma_f32 v[94:95], v[72:73], v[106:107], v[94:95]
	v_pk_fma_f32 v[34:35], v[48:49], v[104:105], v[34:35]
	v_pk_fma_f32 v[74:75], v[78:79], v[90:91], v[74:75]
	v_pk_fma_f32 v[94:95], v[80:81], v[86:87], v[94:95]
	v_pk_fma_f32 v[34:35], v[52:53], v[88:89], v[34:35]
	v_lshlrev_b32_e32 v96, 16, v37
	v_and_b32_e32 v97, 0xffff0000, v37
	v_pk_fma_f32 v[74:75], v[82:83], v[76:77], v[74:75]
	v_pk_fma_f32 v[94:95], v[84:85], v[98:99], v[94:95]
	v_pk_fma_f32 v[112:113], v[56:57], v[96:97], v[34:35]
	v_cvt_pk_bf16_f32 v34, v74, v75
	v_cvt_pk_bf16_f32 v35, v94, v95
	v_cvt_pk_bf16_f32 v36, v110, v111
	v_cvt_pk_bf16_f32 v37, v112, v113
	s_nop 1
	ds_write_b128 v158, v[34:37] offset:1024
	v_pk_fma_f32 v[34:35], v[62:63], v[92:93], v[58:59]
	v_pk_fma_f32 v[36:37], v[64:65], v[106:107], v[60:61]
	v_pk_fma_f32 v[92:93], v[38:39], v[108:109], v[42:43]
	v_pk_fma_f32 v[104:105], v[40:41], v[104:105], v[44:45]
	v_pk_fma_f32 v[34:35], v[70:71], v[90:91], v[34:35]
	v_pk_fma_f32 v[36:37], v[72:73], v[86:87], v[36:37]
	v_pk_fma_f32 v[92:93], v[46:47], v[102:103], v[92:93]
	v_pk_fma_f32 v[104:105], v[48:49], v[88:89], v[104:105]
	v_pk_fma_f32 v[34:35], v[78:79], v[76:77], v[34:35]
	v_lshlrev_b32_e32 v74, 16, v66
	v_and_b32_e32 v75, 0xffff0000, v66
	v_pk_fma_f32 v[36:37], v[80:81], v[98:99], v[36:37]
	v_lshlrev_b32_e32 v66, 16, v67
	v_and_b32_e32 v67, 0xffff0000, v67
	v_pk_fma_f32 v[92:93], v[50:51], v[100:101], v[92:93]
	v_lshlrev_b32_e32 v94, 16, v68
	v_and_b32_e32 v95, 0xffff0000, v68
	v_pk_fma_f32 v[104:105], v[52:53], v[96:97], v[104:105]
	v_lshlrev_b32_e32 v68, 16, v69
	v_and_b32_e32 v69, 0xffff0000, v69
	v_pk_fma_f32 v[34:35], v[82:83], v[74:75], v[34:35]
	v_pk_fma_f32 v[36:37], v[84:85], v[66:67], v[36:37]
	v_pk_fma_f32 v[92:93], v[54:55], v[94:95], v[92:93]
	v_pk_fma_f32 v[104:105], v[56:57], v[68:69], v[104:105]
	v_cvt_pk_bf16_f32 v34, v34, v35
	v_cvt_pk_bf16_f32 v35, v36, v37
	v_cvt_pk_bf16_f32 v36, v92, v93
	v_cvt_pk_bf16_f32 v37, v104, v105
	s_nop 1
	ds_write_b128 v158, v[34:37] offset:1152
	v_pk_fma_f32 v[34:35], v[62:63], v[90:91], v[58:59]
	v_lshlrev_b32_e32 v36, 16, v26
	v_and_b32_e32 v37, 0xffff0000, v26
	v_lshlrev_b32_e32 v90, 16, v27
	v_and_b32_e32 v91, 0xffff0000, v27
	v_pk_fma_f32 v[26:27], v[38:39], v[102:103], v[42:43]
	v_lshlrev_b32_e32 v92, 16, v28
	v_pk_fma_f32 v[26:27], v[46:47], v[100:101], v[26:27]
	v_and_b32_e32 v93, 0xffff0000, v28
	v_pk_fma_f32 v[26:27], v[50:51], v[94:95], v[26:27]
	v_pk_fma_f32 v[86:87], v[64:65], v[86:87], v[60:61]
; #define LAS __attribute__((address_space(3)))
; __device__ __forceinline__ unsigned pk2(float lo, float hi) { const f32x2 v = {lo, hi}; return __builtin_bit_cast(unsigned, __builtin_convertvector(v, bf16x2_t)); }
; __device__ __forceinline__ void lru_prepass(const Args& a, int l, int lane, int tok0, int nb, LAS unsigned char* xt) {
;     ...
;     for (int i = 0; i < 16; ++i) { float acc[8];
; #pragma unroll
;         for (int e = 0; e < 8; ++e) acc[e] = cbv[e];
; #pragma unroll
;         for (int tp = 0; tp < 4; ++tp) { const v4u xx = x[i + tp];
;             acc[0] += cw[tp][0] * bflo(xx.x); acc[1] += cw[tp][1] * bfhi(xx.x); acc[2] += cw[tp][2] * bflo(xx.y); acc[3] += cw[tp][3] * bfhi(xx.y);
;             acc[4] += cw[tp][4] * bflo(xx.z); acc[5] += cw[tp][5] * bfhi(xx.z); acc[6] += cw[tp][6] * bflo(xx.w); acc[7] += cw[tp][7] * bfhi(xx.w); }
;         v4u o; o.x = pk2(acc[0], acc[1]); o.y = pk2(acc[2], acc[3]); o.z = pk2(acc[4], acc[5]); o.w = pk2(acc[6], acc[7]);
;         *(LAS v4u*)(xt + (16 * tg + i) * 128 + oc * 16) = o; asm volatile("s_nop 1" ::: "memory"); }
	v_pk_fma_f32 v[102:103], v[54:55], v[92:93], v[26:27]
	v_pk_fma_f32 v[26:27], v[40:41], v[88:89], v[44:45]
	v_pk_fma_f32 v[34:35], v[70:71], v[76:77], v[34:35]
	v_pk_fma_f32 v[86:87], v[72:73], v[98:99], v[86:87]
	v_pk_fma_f32 v[26:27], v[48:49], v[96:97], v[26:27]
	v_pk_fma_f32 v[34:35], v[78:79], v[74:75], v[34:35]
	v_pk_fma_f32 v[86:87], v[80:81], v[66:67], v[86:87]
	v_pk_fma_f32 v[26:27], v[52:53], v[68:69], v[26:27]
	v_lshlrev_b32_e32 v88, 16, v29
	v_and_b32_e32 v89, 0xffff0000, v29
	v_pk_fma_f32 v[34:35], v[82:83], v[36:37], v[34:35]
	v_pk_fma_f32 v[86:87], v[84:85], v[90:91], v[86:87]
	v_pk_fma_f32 v[104:105], v[56:57], v[88:89], v[26:27]
	v_cvt_pk_bf16_f32 v26, v34, v35
	v_cvt_pk_bf16_f32 v27, v86, v87
	v_cvt_pk_bf16_f32 v28, v102, v103
	v_cvt_pk_bf16_f32 v29, v104, v105
	s_nop 1
	ds_write_b128 v158, v[26:29] offset:1280
	v_pk_fma_f32 v[26:27], v[62:63], v[76:77], v[58:59]
	v_pk_fma_f32 v[28:29], v[64:65], v[98:99], v[60:61]
	v_pk_fma_f32 v[76:77], v[38:39], v[100:101], v[42:43]
	v_pk_fma_f32 v[96:97], v[40:41], v[96:97], v[44:45]
	v_pk_fma_f32 v[26:27], v[70:71], v[74:75], v[26:27]
	v_pk_fma_f32 v[28:29], v[72:73], v[66:67], v[28:29]
	v_pk_fma_f32 v[76:77], v[46:47], v[94:95], v[76:77]
	v_pk_fma_f32 v[96:97], v[48:49], v[68:69], v[96:97]
	v_pk_fma_f32 v[26:27], v[78:79], v[36:37], v[26:27]
	v_lshlrev_b32_e32 v34, 16, v30
	v_and_b32_e32 v35, 0xffff0000, v30
	v_pk_fma_f32 v[28:29], v[80:81], v[90:91], v[28:29]
	v_lshlrev_b32_e32 v30, 16, v31
	v_and_b32_e32 v31, 0xffff0000, v31
	v_pk_fma_f32 v[76:77], v[50:51], v[92:93], v[76:77]
	v_lshlrev_b32_e32 v86, 16, v32
	v_and_b32_e32 v87, 0xffff0000, v32
	v_pk_fma_f32 v[96:97], v[52:53], v[88:89], v[96:97]
	v_lshlrev_b32_e32 v32, 16, v33
	v_and_b32_e32 v33, 0xffff0000, v33
	v_pk_fma_f32 v[26:27], v[82:83], v[34:35], v[26:27]
	v_pk_fma_f32 v[28:29], v[84:85], v[30:31], v[28:29]
	v_pk_fma_f32 v[76:77], v[54:55], v[86:87], v[76:77]
	v_pk_fma_f32 v[96:97], v[56:57], v[32:33], v[96:97]
	v_cvt_pk_bf16_f32 v26, v26, v27
	v_cvt_pk_bf16_f32 v27, v28, v29
	v_cvt_pk_bf16_f32 v28, v76, v77
	v_cvt_pk_bf16_f32 v29, v96, v97
	s_nop 1
	ds_write_b128 v158, v[26:29] offset:1408
	v_pk_fma_f32 v[26:27], v[62:63], v[74:75], v[58:59]
	v_lshlrev_b32_e32 v28, 16, v18
	v_and_b32_e32 v29, 0xffff0000, v18
	v_lshlrev_b32_e32 v74, 16, v19
	v_and_b32_e32 v75, 0xffff0000, v19
	v_pk_fma_f32 v[18:19], v[38:39], v[94:95], v[42:43]
	v_lshlrev_b32_e32 v76, 16, v20
	v_pk_fma_f32 v[18:19], v[46:47], v[92:93], v[18:19]
	v_and_b32_e32 v77, 0xffff0000, v20
	v_pk_fma_f32 v[18:19], v[50:51], v[86:87], v[18:19]
	v_pk_fma_f32 v[66:67], v[64:65], v[66:67], v[60:61]
	v_pk_fma_f32 v[94:95], v[54:55], v[76:77], v[18:19]
	v_pk_fma_f32 v[18:19], v[40:41], v[68:69], v[44:45]
	v_pk_fma_f32 v[26:27], v[70:71], v[36:37], v[26:27]
	v_pk_fma_f32 v[66:67], v[72:73], v[90:91], v[66:67]
	v_pk_fma_f32 v[18:19], v[48:49], v[88:89], v[18:19]
	v_pk_fma_f32 v[26:27], v[78:79], v[34:35], v[26:27]
	v_pk_fma_f32 v[66:67], v[80:81], v[30:31], v[66:67]
	v_pk_fma_f32 v[18:19], v[52:53], v[32:33], v[18:19]
	v_lshlrev_b32_e32 v68, 16, v21
	v_and_b32_e32 v69, 0xffff0000, v21
	v_pk_fma_f32 v[26:27], v[82:83], v[28:29], v[26:27]
	v_pk_fma_f32 v[66:67], v[84:85], v[74:75], v[66:67]
	v_pk_fma_f32 v[96:97], v[56:57], v[68:69], v[18:19]
	v_cvt_pk_bf16_f32 v18, v26, v27
	v_cvt_pk_bf16_f32 v19, v66, v67
	v_cvt_pk_bf16_f32 v20, v94, v95
	v_cvt_pk_bf16_f32 v21, v96, v97
	s_nop 1
	ds_write_b128 v158, v[18:21] offset:1536
	v_pk_fma_f32 v[18:19], v[62:63], v[36:37], v[58:59]
	v_pk_fma_f32 v[20:21], v[64:65], v[90:91], v[60:61]
	v_pk_fma_f32 v[36:37], v[38:39], v[92:93], v[42:43]
	v_pk_fma_f32 v[88:89], v[40:41], v[88:89], v[44:45]
	v_pk_fma_f32 v[18:19], v[70:71], v[34:35], v[18:19]
	v_pk_fma_f32 v[20:21], v[72:73], v[30:31], v[20:21]
	v_pk_fma_f32 v[36:37], v[46:47], v[86:87], v[36:37]
	v_pk_fma_f32 v[88:89], v[48:49], v[32:33], v[88:89]
	v_pk_fma_f32 v[18:19], v[78:79], v[28:29], v[18:19]
	v_lshlrev_b32_e32 v26, 16, v22
	v_and_b32_e32 v27, 0xffff0000, v22
	v_pk_fma_f32 v[20:21], v[80:81], v[74:75], v[20:21]
	v_lshlrev_b32_e32 v22, 16, v23
	v_and_b32_e32 v23, 0xffff0000, v23
	v_pk_fma_f32 v[36:37], v[50:51], v[76:77], v[36:37]
	v_lshlrev_b32_e32 v66, 16, v24
	v_and_b32_e32 v67, 0xffff0000, v24
	v_pk_fma_f32 v[88:89], v[52:53], v[68:69], v[88:89]
	v_lshlrev_b32_e32 v24, 16, v25
	v_and_b32_e32 v25, 0xffff0000, v25
	v_pk_fma_f32 v[18:19], v[82:83], v[26:27], v[18:19]
	v_pk_fma_f32 v[20:21], v[84:85], v[22:23], v[20:21]
	v_pk_fma_f32 v[36:37], v[54:55], v[66:67], v[36:37]
	v_pk_fma_f32 v[88:89], v[56:57], v[24:25], v[88:89]
	v_cvt_pk_bf16_f32 v18, v18, v19
	v_cvt_pk_bf16_f32 v19, v20, v21
	v_cvt_pk_bf16_f32 v20, v36, v37
	v_cvt_pk_bf16_f32 v21, v88, v89
	s_nop 1
	ds_write_b128 v158, v[18:21] offset:1664
	v_pk_fma_f32 v[18:19], v[62:63], v[34:35], v[58:59]
	v_lshlrev_b32_e32 v20, 16, v10
	v_and_b32_e32 v21, 0xffff0000, v10
	v_lshlrev_b32_e32 v34, 16, v11
	v_and_b32_e32 v35, 0xffff0000, v11
	v_pk_fma_f32 v[10:11], v[38:39], v[86:87], v[42:43]
	v_lshlrev_b32_e32 v36, 16, v12
	v_pk_fma_f32 v[10:11], v[46:47], v[76:77], v[10:11]
	v_and_b32_e32 v37, 0xffff0000, v12
	v_pk_fma_f32 v[10:11], v[50:51], v[66:67], v[10:11]
	v_pk_fma_f32 v[30:31], v[64:65], v[30:31], v[60:61]
	v_pk_fma_f32 v[86:87], v[54:55], v[36:37], v[10:11]
	v_pk_fma_f32 v[10:11], v[40:41], v[32:33], v[44:45]
	v_pk_fma_f32 v[18:19], v[70:71], v[28:29], v[18:19]
	v_pk_fma_f32 v[30:31], v[72:73], v[74:75], v[30:31]
	v_pk_fma_f32 v[10:11], v[48:49], v[68:69], v[10:11]
	v_pk_fma_f32 v[18:19], v[78:79], v[26:27], v[18:19]
	v_pk_fma_f32 v[30:31], v[80:81], v[22:23], v[30:31]
	v_pk_fma_f32 v[10:11], v[52:53], v[24:25], v[10:11]
; #define LAS __attribute__((address_space(3)))
; #define LDS_WAIT() asm volatile("s_waitcnt lgkmcnt(0)" ::: "memory")
; template <int MODE, int DIR> __device__ __forceinline__ void lru_dir(const Args& a, int l, int lane, int tok0, int nb, int half, const LAS unsigned char* xt, bf16* hf) {
;     ...
;     pg8::bf16x8 wa[2][2], wx[2][2];
;     { const pg8::bf16x8* wp = (const pg8::bf16x8*)(a.ws + WS_TWF) + (size_t)((DIR * 8 + nb) * 2) * 4 * 2 * 64 + lane;
; #pragma unroll
;       for (int c2 = 0; c2 < 2; ++c2)
; #pragma unroll
;           for (int ks = 0; ks < 2; ++ks) { wa[c2][ks] = wp[((2 * half + c2) * 2 + ks) * 64]; wx[c2][ks] = wp[(8 + (2 * half + c2) * 2 + ks) * 64]; } }
;     pg8::bf16x8 idn[2];
; #pragma unroll
;     for (int hf = 0; hf < 2; ++hf) { v4u w;
; #pragma unroll
;         for (int jj = 0; jj < 4; ++jj) { const int k0 = 8 * g + 2 * jj; w[jj] = ((k0 == 16 * hf + n) ? 0x3f80u : 0u) | ((k0 + 1 == 16 * hf + n) ? 0x3f800000u : 0u); }
;         idn[hf] = __builtin_bit_cast(pg8::bf16x8, w); }
;     float ba[2], bx[2], ls8[2], h[2], P[2];
;     const int cch = 64 * nb + 32 * half + n;
; #pragma unroll
;     for (int c2 = 0; c2 < 2; ++c2) { const int c = cch + 16 * c2; const size_t ix = (size_t)(l * 2 + DIR) * 512 + c;
;         ba[c2] = -1.4426950408889634f * a.in[I_LBA][ix]; bx[c2] = -1.4426950408889634f * a.in[I_LBX][ix]; ls8[c2] = (-8.f * 1.4426950408889634f) * log1pf(__expf(-a.in[I_LAM][ix]));
;         h[c2] = MODE ? cin[((size_t)ch * 2 + DIR) * 512 + c] : 0.f; P[c2] = 1.f; }
; __device__ __forceinline__ void lru_prepass(const Args& a, int l, int lane, int tok0, int nb, LAS unsigned char* xt) {
;     ...
;     for (int i = 0; i < 16; ++i) { float acc[8];
; #pragma unroll
;         for (int e = 0; e < 8; ++e) acc[e] = cbv[e];
; #pragma unroll
;         for (int tp = 0; tp < 4; ++tp) { const v4u xx = x[i + tp];
;             acc[0] += cw[tp][0] * bflo(xx.x); acc[1] += cw[tp][1] * bfhi(xx.x); acc[2] += cw[tp][2] * bflo(xx.y); acc[3] += cw[tp][3] * bfhi(xx.y);
;             acc[4] += cw[tp][4] * bflo(xx.z); acc[5] += cw[tp][5] * bfhi(xx.z); acc[6] += cw[tp][6] * bflo(xx.w); acc[7] += cw[tp][7] * bfhi(xx.w); }
;         v4u o; o.x = pk2(acc[0], acc[1]); o.y = pk2(acc[2], acc[3]); o.z = pk2(acc[4], acc[5]); o.w = pk2(acc[6], acc[7]);
;         *(LAS v4u*)(xt + (16 * tg + i) * 128 + oc * 16) = o; asm volatile("s_nop 1" ::: "memory"); }
;     LDS_WAIT();
	v_lshlrev_b32_e32 v32, 16, v13
	v_and_b32_e32 v33, 0xffff0000, v13
	v_pk_fma_f32 v[18:19], v[82:83], v[20:21], v[18:19]
	v_pk_fma_f32 v[30:31], v[84:85], v[34:35], v[30:31]
	v_pk_fma_f32 v[88:89], v[56:57], v[32:33], v[10:11]
	v_cvt_pk_bf16_f32 v10, v18, v19
	v_cvt_pk_bf16_f32 v11, v30, v31
	v_cvt_pk_bf16_f32 v12, v86, v87
	v_cvt_pk_bf16_f32 v13, v88, v89
	s_nop 1
	ds_write_b128 v159, v[10:13]
	v_pk_fma_f32 v[10:11], v[62:63], v[28:29], v[58:59]
	v_lshlrev_b32_e32 v12, 16, v14
	v_pk_fma_f32 v[10:11], v[70:71], v[26:27], v[10:11]
	v_and_b32_e32 v13, 0xffff0000, v14
	v_pk_fma_f32 v[10:11], v[78:79], v[20:21], v[10:11]
	v_lshlrev_b32_e32 v14, 16, v15
	v_pk_fma_f32 v[10:11], v[82:83], v[12:13], v[10:11]
	v_pk_fma_f32 v[12:13], v[64:65], v[74:75], v[60:61]
	v_and_b32_e32 v15, 0xffff0000, v15
	v_pk_fma_f32 v[12:13], v[72:73], v[22:23], v[12:13]
	v_lshlrev_b32_e32 v18, 16, v16
	v_pk_fma_f32 v[12:13], v[80:81], v[34:35], v[12:13]
	v_and_b32_e32 v19, 0xffff0000, v16
	v_pk_fma_f32 v[12:13], v[84:85], v[14:15], v[12:13]
	v_pk_fma_f32 v[14:15], v[38:39], v[76:77], v[42:43]
	v_lshlrev_b32_e32 v16, 16, v17
	v_pk_fma_f32 v[14:15], v[46:47], v[66:67], v[14:15]
	v_and_b32_e32 v17, 0xffff0000, v17
	v_pk_fma_f32 v[14:15], v[50:51], v[36:37], v[14:15]
	v_cvt_pk_bf16_f32 v10, v10, v11
	v_pk_fma_f32 v[14:15], v[54:55], v[18:19], v[14:15]
	v_pk_fma_f32 v[18:19], v[40:41], v[68:69], v[44:45]
	v_cvt_pk_bf16_f32 v11, v12, v13
	v_pk_fma_f32 v[18:19], v[48:49], v[24:25], v[18:19]
	v_cvt_pk_bf16_f32 v12, v14, v15
	v_pk_fma_f32 v[18:19], v[52:53], v[32:33], v[18:19]
	v_or_b32_e32 v66, s1, v128
	v_pk_fma_f32 v[16:17], v[56:57], v[16:17], v[18:19]
	s_nop 1
	v_or_b32_e32 v190, s51, v66
	v_cvt_pk_bf16_f32 v13, v16, v17
	ds_write_b128 v160, v[10:13]
	s_nop 1
	v_lshlrev_b64 v[10:11], 2, v[190:191]
	s_waitcnt lgkmcnt(0)
	v_lshl_add_u64 v[12:13], s[14:15], 0, v[10:11]
	global_load_dword v44, v[12:13], off
	v_lshl_add_u64 v[12:13], s[8:9], 0, v[10:11]
	v_lshl_add_u64 v[10:11], s[12:13], 0, v[10:11]
	global_load_dword v46, v[10:11], off
	global_load_dword v45, v[12:13], off
	v_or_b32_e32 v42, s4, v1
	v_ashrrev_i32_e32 v43, 31, v42
	v_lshlrev_b64 v[68:69], 12, v[42:43]
	v_lshl_add_u64 v[10:11], v[142:143], 0, s[82:83]
	s_lshl_b32 s82, s36, 12
	v_lshl_add_u64 v[30:31], v[10:11], 0, s[82:83]
	v_add_co_u32_e32 v38, vcc, s5, v30
	v_readlane_b32 s4, v252, 47
	v_readlane_b32 s5, v252, 48
	v_addc_co_u32_e32 v39, vcc, 0, v31, vcc
	v_lshlrev_b32_e32 v190, 2, v66
	global_load_dwordx4 v[10:13], v[30:31], off
	global_load_dwordx4 v[14:17], v[30:31], off offset:1024
	global_load_dwordx4 v[18:21], v[38:39], off
	global_load_dwordx4 v[22:25], v[38:39], off offset:1024
	global_load_dwordx4 v[26:29], v[30:31], off offset:2048
	s_nop 0
	global_load_dwordx4 v[30:33], v[30:31], off offset:3072
	s_nop 0
	global_load_dwordx4 v[34:37], v[38:39], off offset:2048
	s_nop 0
	global_load_dwordx4 v[38:41], v[38:39], off offset:3072
	s_lshl_b32 s1, s0, 10
	s_lshl_b32 s0, s36, 8
	s_cmp_eq_u32 s36, 0
	s_cselect_b64 s[92:93], -1, 0
	v_lshl_add_u64 v[78:79], v[146:147], 0, s[38:39]
	v_mov_b32_e32 v85, v157
	s_waitcnt vmcnt(10)
	v_mul_f32_e32 v42, 0xbfb8aa3b, v44
	v_exp_f32_e32 v47, v42
	v_lshl_add_u64 v[42:43], s[4:5], 0, v[68:69]
	s_waitcnt vmcnt(9)
	v_mul_f32_e32 v80, 0xbfb8aa3b, v46
	s_waitcnt vmcnt(8)
	v_mul_f32_e32 v67, 0xbfb8aa3b, v45
	v_add_f32_e32 v46, 1.0, v47
	v_add_f32_e32 v44, -1.0, v46
	v_sub_f32_e32 v45, v44, v46
	v_add_f32_e32 v45, 1.0, v45
	v_sub_f32_e32 v44, v47, v44
	v_add_f32_e32 v48, v44, v45
	v_frexp_mant_f32_e32 v49, v46
	v_cvt_f64_f32_e32 v[44:45], v46
	s_mov_b32 s4, 0x3f2aaaab
	v_frexp_exp_i32_f64_e32 v44, v[44:45]
	v_cmp_gt_f32_e32 vcc, s4, v49
	v_lshl_add_u64 v[42:43], v[42:43], 0, v[190:191]
	v_add_u32_e32 v190, s51, v66
	v_subbrev_co_u32_e32 v49, vcc, 0, v44, vcc
	v_sub_u32_e32 v44, 0, v49
	v_ldexp_f32 v45, v46, v44
	v_add_f32_e32 v46, -1.0, v45
	v_add_f32_e32 v51, 1.0, v45
	v_ldexp_f32 v44, v48, v44
	v_add_f32_e32 v48, 1.0, v46
	v_add_f32_e32 v52, -1.0, v51
	v_sub_f32_e32 v48, v45, v48
	v_sub_f32_e32 v45, v45, v52
	v_add_f32_e32 v48, v44, v48
	v_add_f32_e32 v44, v44, v45
	v_add_f32_e32 v52, v51, v44
	v_rcp_f32_e32 v53, v52
	v_add_f32_e32 v50, v46, v48
	v_sub_f32_e32 v46, v50, v46
	v_sub_f32_e32 v45, v52, v51
	v_mul_f32_e32 v51, v50, v53
	v_sub_f32_e32 v46, v48, v46
	v_sub_f32_e32 v48, v44, v45
	v_mul_f32_e32 v44, v52, v51
	v_fma_f32 v54, v51, v52, -v44
	v_fmac_f32_e32 v54, v51, v48
	v_add_f32_e32 v55, v44, v54
	v_sub_f32_e32 v56, v55, v44
	v_lshlrev_b64 v[44:45], 2, v[190:191]
	v_lshl_add_u64 v[70:71], s[14:15], 0, v[44:45]
	global_load_dword v58, v[70:71], off offset:64
	v_lshl_add_u64 v[74:75], s[12:13], 0, v[44:45]
	v_lshl_add_u64 v[72:73], s[8:9], 0, v[44:45]
	global_load_dword v44, v[74:75], off offset:64
	v_sub_f32_e32 v57, v50, v55
	v_sub_f32_e32 v50, v50, v57
	v_sub_f32_e32 v45, v50, v55
	v_add_f32_e32 v45, v46, v45
	v_sub_f32_e32 v46, v56, v54
	v_add_f32_e32 v45, v46, v45
	v_add_f32_e32 v46, v57, v45
	v_mul_f32_e32 v50, v53, v46
	v_mul_f32_e32 v54, v52, v50
	v_fma_f32 v52, v50, v52, -v54
	v_fmac_f32_e32 v52, v50, v48
	v_sub_f32_e32 v48, v57, v46
	v_add_f32_e32 v45, v45, v48
	v_add_f32_e32 v48, v54, v52
	v_sub_f32_e32 v55, v46, v48
	v_sub_f32_e32 v46, v46, v55
	v_sub_f32_e32 v54, v48, v54
	v_sub_f32_e32 v46, v46, v48
	v_add_f32_e32 v45, v45, v46
	v_sub_f32_e32 v46, v54, v52
	v_cvt_f32_i32_e32 v49, v49
	v_add_f32_e32 v45, v46, v45
	v_add_f32_e32 v46, v51, v50
	v_add_f32_e32 v45, v55, v45
	v_sub_f32_e32 v48, v46, v51
	v_mul_f32_e32 v45, v53, v45
	v_sub_f32_e32 v48, v50, v48
	v_add_f32_e32 v45, v48, v45
	v_mul_f32_e32 v52, 0x3f317218, v49
	s_mov_b32 s5, 0x3f317218
	v_add_f32_e32 v48, v46, v45
	v_fma_f32 v53, v49, s5, -v52
	v_mul_f32_e32 v50, v48, v48
	v_fmac_f32_e32 v53, 0xb102e308, v49
	v_sub_f32_e32 v46, v48, v46
	v_fmamk_f32 v51, v50, 0x3e9b6dac, v228
	v_sub_f32_e32 v45, v45, v46
	v_add_f32_e32 v46, v52, v53
	v_fmaak_f32 v51, v50, v51, 0x3f2aaada
	v_sub_f32_e32 v49, v46, v52
	v_ldexp_f32 v52, v48, 1
	v_mul_f32_e32 v48, v48, v50
	v_mul_f32_e32 v48, v48, v51
	v_add_f32_e32 v50, v52, v48
	v_sub_f32_e32 v51, v50, v52
	v_ldexp_f32 v45, v45, 1
	v_sub_f32_e32 v48, v48, v51
	v_add_f32_e32 v45, v45, v48
	v_add_f32_e32 v48, v50, v45
	v_sub_f32_e32 v50, v48, v50
	v_sub_f32_e32 v45, v45, v50
	v_add_f32_e32 v50, v46, v48
	v_sub_f32_e32 v51, v50, v46
	v_sub_f32_e32 v52, v50, v51
	v_sub_f32_e32 v49, v53, v49
	v_sub_f32_e32 v46, v46, v52
	v_sub_f32_e32 v48, v48, v51
	v_add_f32_e32 v46, v48, v46
	v_add_f32_e32 v48, v49, v45
	global_load_dword v59, v[72:73], off offset:64
	v_sub_f32_e32 v51, v48, v49
	v_sub_f32_e32 v52, v48, v51
	v_add_f32_e32 v46, v48, v46
	global_load_dword v76, v[42:43], off
	global_load_dword v77, v[42:43], off offset:64
	v_sub_f32_e32 v49, v49, v52
	v_sub_f32_e32 v45, v45, v51
	v_add_f32_e32 v48, v50, v46
	v_add_f32_e32 v45, v45, v49
	v_sub_f32_e32 v49, v48, v50
	v_sub_f32_e32 v46, v46, v49
	v_add_f32_e32 v45, v45, v46
	v_add_f32_e32 v45, v48, v45
	v_cmp_neq_f32_e32 vcc, s6, v47
	s_waitcnt vmcnt(4)
; #define LAS __attribute__((address_space(3)))
; template <int MODE, int DIR> __device__ __forceinline__ void lru_dir(const Args& a, int l, int lane, int tok0, int nb, int half, const LAS unsigned char* xt, bf16* hf) {
;     ...
;     for (int c2 = 0; c2 < 2; ++c2) { const int c = cch + 16 * c2; const size_t ix = (size_t)(l * 2 + DIR) * 512 + c;
;         ba[c2] = -1.4426950408889634f * a.in[I_LBA][ix]; bx[c2] = -1.4426950408889634f * a.in[I_LBX][ix]; ls8[c2] = (-8.f * 1.4426950408889634f) * log1pf(__expf(-a.in[I_LAM][ix]));
;         h[c2] = MODE ? cin[((size_t)ch * 2 + DIR) * 512 + c] : 0.f; P[c2] = 1.f; }
;     ...
;         const pg8::bf16x8 a0 = *(const LAS pg8::bf16x8*)(xa + t4 * 128), a1 = *(const LAS pg8::bf16x8*)(xa + t4 * 128 + 64);
;         const pg8::bf16x8 ah = half ? a1 : a0;
;         f32x4 pa[2], px[2], xd[2];
; #pragma unroll
;         for (int c2 = 0; c2 < 2; ++c2) { const f32x4 z4 = (f32x4){0.f, 0.f, 0.f, 0.f};
;             pa[c2] = __builtin_amdgcn_mfma_f32_16x16x32_bf16(a0, wa[c2][0], z4, 0, 0, 0); pa[c2] = __builtin_amdgcn_mfma_f32_16x16x32_bf16(a1, wa[c2][1], pa[c2], 0, 0, 0);
;             px[c2] = __builtin_amdgcn_mfma_f32_16x16x32_bf16(a0, wx[c2][0], z4, 0, 0, 0); px[c2] = __builtin_amdgcn_mfma_f32_16x16x32_bf16(a1, wx[c2][1], px[c2], 0, 0, 0);
;             xd[c2] = __builtin_amdgcn_mfma_f32_16x16x32_bf16(ah, idn[c2], z4, 0, 0, 0); }
	v_mul_f32_e32 v46, 0xbfb8aa3b, v58
	v_exp_f32_e32 v46, v46
	v_cndmask_b32_e32 v45, v231, v45, vcc
	v_cmp_ngt_f32_e32 vcc, -1.0, v47
	s_waitcnt vmcnt(3)
	v_mul_f32_e32 v83, 0xbfb8aa3b, v44
	s_waitcnt vmcnt(2)
	v_mul_f32_e32 v82, 0xbfb8aa3b, v59
	v_cndmask_b32_e32 v45, v232, v45, vcc
	v_cmp_neq_f32_e32 vcc, -1.0, v47
	s_nop 1
	v_cndmask_b32_e32 v45, v233, v45, vcc
	v_cmp_lt_f32_e64 vcc, |v47|, s7
	s_nop 1
	v_cndmask_b32_e32 v45, v45, v47, vcc
	v_add_f32_e32 v47, 1.0, v46
	v_add_f32_e32 v44, -1.0, v47
	v_mul_f32_e32 v81, 0xc138aa3b, v45
	v_sub_f32_e32 v45, v44, v47
	v_add_f32_e32 v45, 1.0, v45
	v_sub_f32_e32 v44, v46, v44
	v_add_f32_e32 v48, v44, v45
	v_frexp_mant_f32_e32 v49, v47
	v_cvt_f64_f32_e32 v[44:45], v47
	v_frexp_exp_i32_f64_e32 v44, v[44:45]
	v_cmp_gt_f32_e32 vcc, s4, v49
	s_nop 1
	v_subbrev_co_u32_e32 v44, vcc, 0, v44, vcc
	v_sub_u32_e32 v45, 0, v44
	v_ldexp_f32 v47, v47, v45
	v_ldexp_f32 v45, v48, v45
	v_add_f32_e32 v48, -1.0, v47
	v_add_f32_e32 v51, 1.0, v47
	v_add_f32_e32 v49, 1.0, v48
	v_add_f32_e32 v52, -1.0, v51
	v_sub_f32_e32 v49, v47, v49
	v_sub_f32_e32 v47, v47, v52
	v_add_f32_e32 v49, v45, v49
	v_add_f32_e32 v45, v45, v47
	v_add_f32_e32 v47, v51, v45
	v_rcp_f32_e32 v52, v47
	v_add_f32_e32 v50, v48, v49
	v_sub_f32_e32 v48, v50, v48
	v_sub_f32_e32 v48, v49, v48
	v_sub_f32_e32 v49, v47, v51
	v_sub_f32_e32 v45, v45, v49
	v_mul_f32_e32 v49, v50, v52
	v_mul_f32_e32 v51, v47, v49
	v_fma_f32 v53, v49, v47, -v51
	v_fmac_f32_e32 v53, v49, v45
	v_add_f32_e32 v54, v51, v53
	v_sub_f32_e32 v55, v50, v54
	v_sub_f32_e32 v50, v50, v55
	v_sub_f32_e32 v51, v54, v51
	v_sub_f32_e32 v50, v50, v54
	v_add_f32_e32 v48, v48, v50
	v_sub_f32_e32 v42, v51, v53
	v_add_f32_e32 v42, v42, v48
	v_add_f32_e32 v43, v55, v42
	v_mul_f32_e32 v48, v52, v43
	v_mul_f32_e32 v50, v47, v48
	v_fma_f32 v47, v48, v47, -v50
	v_fmac_f32_e32 v47, v48, v45
	v_sub_f32_e32 v45, v55, v43
	v_add_f32_e32 v42, v42, v45
	v_add_f32_e32 v45, v50, v47
	v_sub_f32_e32 v51, v43, v45
	v_sub_f32_e32 v43, v43, v51
	v_sub_f32_e32 v50, v45, v50
	v_sub_f32_e32 v43, v43, v45
	v_add_f32_e32 v42, v42, v43
	v_sub_f32_e32 v43, v50, v47
	v_cvt_f32_i32_e32 v44, v44
	v_add_f32_e32 v42, v43, v42
	v_add_f32_e32 v43, v49, v48
	v_add_f32_e32 v42, v51, v42
	v_sub_f32_e32 v45, v43, v49
	v_mul_f32_e32 v42, v52, v42
	v_sub_f32_e32 v45, v48, v45
	v_add_f32_e32 v42, v45, v42
	v_mul_f32_e32 v49, 0x3f317218, v44
	v_add_f32_e32 v45, v43, v42
	v_fma_f32 v50, v44, s5, -v49
	v_mul_f32_e32 v47, v45, v45
	v_fmac_f32_e32 v50, 0xb102e308, v44
	v_sub_f32_e32 v43, v45, v43
	v_fmamk_f32 v48, v47, 0x3e9b6dac, v228
	v_sub_f32_e32 v42, v42, v43
	v_add_f32_e32 v43, v49, v50
	v_fmaak_f32 v48, v47, v48, 0x3f2aaada
	v_sub_f32_e32 v44, v43, v49
	v_ldexp_f32 v49, v45, 1
	v_mul_f32_e32 v45, v45, v47
	v_mul_f32_e32 v45, v45, v48
	v_add_f32_e32 v47, v49, v45
	v_sub_f32_e32 v48, v47, v49
	v_ldexp_f32 v42, v42, 1
	v_sub_f32_e32 v45, v45, v48
	v_add_f32_e32 v42, v42, v45
	v_add_f32_e32 v45, v47, v42
	v_sub_f32_e32 v47, v45, v47
	v_sub_f32_e32 v42, v42, v47
	v_add_f32_e32 v47, v43, v45
	v_sub_f32_e32 v48, v47, v43
	v_sub_f32_e32 v49, v47, v48
	v_sub_f32_e32 v44, v50, v44
	v_sub_f32_e32 v43, v43, v49
	v_sub_f32_e32 v45, v45, v48
	v_add_f32_e32 v43, v45, v43
	v_add_f32_e32 v45, v44, v42
	v_sub_f32_e32 v48, v45, v44
	v_sub_f32_e32 v49, v45, v48
	v_sub_f32_e32 v44, v44, v49
	v_sub_f32_e32 v42, v42, v48
	v_add_f32_e32 v43, v45, v43
	v_add_f32_e32 v42, v42, v44
	v_add_f32_e32 v44, v47, v43
	v_sub_f32_e32 v45, v44, v47
	v_sub_f32_e32 v43, v43, v45
	v_add_f32_e32 v42, v42, v43
	v_add_f32_e32 v42, v44, v42
	v_cmp_neq_f32_e32 vcc, s6, v46
	s_nop 1
	v_cndmask_b32_e32 v42, v231, v42, vcc
	v_cmp_ngt_f32_e32 vcc, -1.0, v46
	s_nop 1
	v_cndmask_b32_e32 v42, v232, v42, vcc
	v_cmp_neq_f32_e32 vcc, -1.0, v46
	s_nop 1
	v_cndmask_b32_e32 v42, v233, v42, vcc
	v_cmp_lt_f32_e64 vcc, |v46|, s7
	s_nop 1
	v_cndmask_b32_e32 v42, v42, v46, vcc
	v_mul_f32_e32 v84, 0xc138aa3b, v42
	s_waitcnt vmcnt(0)
	v_and_b32_e32 v210, 63, v0
	v_mul_u32_u24_e32 v210, 14, v210
	v_mov_b32_e32 v211, 0
	s_mov_b32 s100, 0xffff0000
.LBB0_714:
	ds_read_b128 v[58:61], v85
	ds_read_b128 v[62:65], v85 offset:64
	s_mov_b32 s4, 0x33000000
	v_add_u32_e32 v85, 0x200, v85
	s_waitcnt lgkmcnt(1)
	v_mfma_f32_16x16x32_bf16 v[42:45], v[58:61], v[10:13], 0
	s_waitcnt lgkmcnt(0)
; #define LAS __attribute__((address_space(3)))
; __device__ __forceinline__ unsigned f2bf(float f) { unsigned u = __builtin_bit_cast(unsigned, f); return (u + 0x7fffu + ((u >> 16) & 1u)) >> 16; }
; __device__ __forceinline__ float frcp(float x) { return __builtin_amdgcn_rcpf(x); }
; __device__ __forceinline__ float fsqrt_(float x) { return __builtin_amdgcn_sqrtf(x); }
; __device__ __forceinline__ float gelu_tanh(float x) { const float x2 = x * x; const float y2 = (2.302208198f * x) * __builtin_fmaf(0.044715f, x2, 1.f); const float e = __builtin_amdgcn_exp2f(y2); return x - x * frcp(e + 1.f); }
; template <int MODE, int DIR> __device__ __forceinline__ void lru_dir(const Args& a, int l, int lane, int tok0, int nb, int half, const LAS unsigned char* xt, bf16* hf) {
;     ...
;         const pg8::bf16x8 a0 = *(const LAS pg8::bf16x8*)(xa + t4 * 128), a1 = *(const LAS pg8::bf16x8*)(xa + t4 * 128 + 64);
;         const pg8::bf16x8 ah = half ? a1 : a0;
;         f32x4 pa[2], px[2], xd[2];
; #pragma unroll
;         for (int c2 = 0; c2 < 2; ++c2) { const f32x4 z4 = (f32x4){0.f, 0.f, 0.f, 0.f};
;             pa[c2] = __builtin_amdgcn_mfma_f32_16x16x32_bf16(a0, wa[c2][0], z4, 0, 0, 0); pa[c2] = __builtin_amdgcn_mfma_f32_16x16x32_bf16(a1, wa[c2][1], pa[c2], 0, 0, 0);
;             px[c2] = __builtin_amdgcn_mfma_f32_16x16x32_bf16(a0, wx[c2][0], z4, 0, 0, 0); px[c2] = __builtin_amdgcn_mfma_f32_16x16x32_bf16(a1, wx[c2][1], px[c2], 0, 0, 0);
;             xd[c2] = __builtin_amdgcn_mfma_f32_16x16x32_bf16(ah, idn[c2], z4, 0, 0, 0); }
; #pragma unroll
;         for (int rr = 0; rr < 4; ++rr) { const int rg = DIR ? 3 - rr : rr;
; #pragma unroll
;             for (int c2 = 0; c2 < 2; ++c2) {
;                 const float r_ = frcp(1.f + __builtin_amdgcn_exp2f(__builtin_fmaf(pa[c2][rg], -1.4426950408889634f, ba[c2]))), i_ = frcp(1.f + __builtin_amdgcn_exp2f(__builtin_fmaf(px[c2][rg], -1.4426950408889634f, bx[c2])));
;                 const float av = __builtin_amdgcn_exp2f(ls8[c2] * r_), mult = fsqrt_(fmaxf(1.f - av * av, 0.f));
;                 h[c2] = av * h[c2] + mult * i_ * xd[c2][rg]; P[c2] *= av;
;                 if (MODE) {
;                     if (DIR == 0) hf[(((t4 >> 2) * 4 + rg) * 2 + c2) * 64 + lane] = (bf16)f2bf(h[c2]);
;                     else yo[(size_t)(t4 + rg) * DM + 16 * c2] = (bf16)f2bf((bf2f(yc[c2][rg]) + h[c2]) * gelu_tanh(bf2f(gc[c2][rg]))); } }
	v_cndmask_b32_e64 v89, v65, v61, s[92:93]
	v_cndmask_b32_e64 v88, v64, v60, s[92:93]
	v_cndmask_b32_e64 v87, v63, v59, s[92:93]
	v_mfma_f32_16x16x32_bf16 v[46:49], v[62:65], v[14:17], v[42:45]
	v_cndmask_b32_e64 v86, v62, v58, s[92:93]
	v_mfma_f32_16x16x32_bf16 v[42:45], v[58:61], v[18:21], 0
	v_mfma_f32_16x16x32_bf16 v[50:53], v[62:65], v[22:25], v[42:45]
	s_nop 4
	v_fmamk_f32 v46, v46, 0xbfb8aa3b, v67
	v_exp_f32_e32 v46, v46
	v_mfma_f32_16x16x32_bf16 v[54:57], v[58:61], v[26:29], 0
	v_add_f32_e32 v46, 1.0, v46
	v_rcp_f32_e32 v46, v46
	v_mfma_f32_16x16x32_bf16 v[58:61], v[58:61], v[34:37], 0
	v_fmamk_f32 v50, v50, 0xbfb8aa3b, v80
	v_exp_f32_e32 v50, v50
	v_mul_f32_e32 v46, v81, v46
	v_mfma_f32_16x16x32_bf16 v[42:45], v[86:89], v[2:5], 0
	v_add_f32_e32 v50, 1.0, v50
	v_rcp_f32_e32 v50, v50
	v_mfma_f32_16x16x32_bf16 v[54:57], v[62:65], v[30:33], v[54:57]
	v_mfma_f32_16x16x32_bf16 v[58:61], v[62:65], v[38:41], v[58:61]
	v_mfma_f32_16x16x32_bf16 v[62:65], v[86:89], v[6:9], 0
	v_exp_f32_e32 v86, v46
	v_mov_b32_e32 v88, v76
	s_nop 0
	v_mov_b32_e32 v89, v42
	v_fma_f32 v46, -v86, v86, 1.0
	v_max_f32_e32 v46, 0, v46
	v_sqrt_f32_e32 v46, v46
	s_nop 0
	v_pk_mov_b32 v[76:77], v[76:77], v[62:63] op_sel:[1,0]
	v_mul_f32_e32 v87, v50, v46
	v_mul_f32_e32 v42, v42, v87
	v_pk_fma_f32 v[86:87], v[88:89], v[86:87], v[42:43] op_sel_hi:[1,1,0]
	v_lshl_add_u64 v[88:89], v[78:79], 0, s[62:63]
	v_bfe_u32 v42, v86, 16, 1
	v_add_co_u32_e32 v88, vcc, s4, v88
	v_add3_u32 v42, v86, v42, s43
	s_nop 0
	v_addc_co_u32_e32 v89, vcc, 0, v89, vcc
	v_lshrrev_b32_e32 v214, 16, v42
	v_lshl_add_u64 v[212:213], v[88:89], 0, v[210:211]
	v_fmamk_f32 v42, v54, 0xbfb8aa3b, v82
	v_exp_f32_e32 v42, v42
	v_fmamk_f32 v46, v58, 0xbfb8aa3b, v83
	v_exp_f32_e32 v46, v46
	s_add_u32 s62, s62, 0x400
	v_add_f32_e32 v42, 1.0, v42
	v_rcp_f32_e32 v42, v42
	v_add_f32_e32 v46, 1.0, v46
	v_rcp_f32_e32 v46, v46
	s_addc_u32 s63, s63, 0
	v_mul_f32_e32 v42, v84, v42
	v_exp_f32_e32 v90, v42
	s_cmpk_lg_i32 s62, 0x2000
	v_fma_f32 v42, -v90, v90, 1.0
	v_max_f32_e32 v42, 0, v42
	v_sqrt_f32_e32 v42, v42
	s_nop 0
	v_mul_f32_e32 v91, v46, v42
	v_mul_f32_e32 v42, v62, v91
	v_pk_fma_f32 v[76:77], v[76:77], v[90:91], v[42:43] op_sel_hi:[1,1,0]
	v_fmamk_f32 v46, v51, 0xbfb8aa3b, v80
	v_bfe_u32 v42, v76, 16, 1
	v_add3_u32 v42, v76, v42, s43
	v_and_or_b32 v214, v42, s100, v214
	v_fmamk_f32 v42, v47, 0xbfb8aa3b, v67
	v_exp_f32_e32 v42, v42
	v_exp_f32_e32 v46, v46
	v_add_f32_e32 v42, 1.0, v42
	v_rcp_f32_e32 v42, v42
	v_add_f32_e32 v46, 1.0, v46
	v_rcp_f32_e32 v46, v46
	v_mul_f32_e32 v42, v81, v42
	v_exp_f32_e32 v47, v42
	s_nop 0
	v_fma_f32 v42, -v47, v47, 1.0
	v_max_f32_e32 v42, 0, v42
	v_sqrt_f32_e32 v42, v42
	v_mul_f32_e32 v50, v47, v86
	v_mul_f32_e32 v42, v46, v42
	v_mov_b32_e32 v46, v43
	v_mov_b32_e32 v43, v86
	v_pk_fma_f32 v[42:43], v[46:47], v[42:43], v[50:51] op_sel_hi:[1,1,0]
	v_fmamk_f32 v46, v59, 0xbfb8aa3b, v83
	v_bfe_u32 v43, v42, 16, 1
	v_add3_u32 v43, v42, v43, s43
	v_lshrrev_b32_e32 v215, 16, v43
	v_fmamk_f32 v43, v55, 0xbfb8aa3b, v82
	v_exp_f32_e32 v43, v43
	v_exp_f32_e32 v46, v46
	v_mov_b32_e32 v51, v76
	v_add_f32_e32 v43, 1.0, v43
	v_rcp_f32_e32 v43, v43
	v_add_f32_e32 v46, 1.0, v46
	v_rcp_f32_e32 v46, v46
	v_mul_f32_e32 v43, v84, v43
	v_exp_f32_e32 v47, v43
	s_nop 0
	v_fma_f32 v43, -v47, v47, 1.0
	v_max_f32_e32 v43, 0, v43
	v_sqrt_f32_e32 v43, v43
	v_mul_f32_e32 v54, v47, v76
	v_mul_f32_e32 v50, v46, v43
	v_mov_b32_e32 v46, v63
	v_pk_fma_f32 v[46:47], v[46:47], v[50:51], v[54:55] op_sel_hi:[1,1,0]
	v_mov_b32_e32 v50, v44
	v_bfe_u32 v43, v46, 16, 1
	v_add3_u32 v43, v46, v43, s43
	v_and_or_b32 v215, v43, s100, v215
	v_fmamk_f32 v43, v48, 0xbfb8aa3b, v67
	v_exp_f32_e32 v43, v43
	v_fmamk_f32 v47, v52, 0xbfb8aa3b, v80
	v_exp_f32_e32 v47, v47
	v_mov_b32_e32 v55, v42
	v_add_f32_e32 v43, 1.0, v43
	v_rcp_f32_e32 v43, v43
	v_add_f32_e32 v47, 1.0, v47
	v_rcp_f32_e32 v47, v47
	v_fmamk_f32 v44, v60, 0xbfb8aa3b, v83
	v_mul_f32_e32 v43, v81, v43
	v_exp_f32_e32 v51, v43
	v_exp_f32_e32 v44, v44
	v_mov_b32_e32 v48, v45
	v_fma_f32 v43, -v51, v51, 1.0
	v_max_f32_e32 v43, 0, v43
	v_sqrt_f32_e32 v43, v43
	v_mul_f32_e32 v42, v51, v42
	v_add_f32_e32 v44, 1.0, v44
	v_rcp_f32_e32 v44, v44
	v_mul_f32_e32 v54, v47, v43
	v_pk_fma_f32 v[42:43], v[50:51], v[54:55], v[42:43] op_sel_hi:[1,1,0]
	v_mov_b32_e32 v50, v64
	v_bfe_u32 v43, v42, 16, 1
	v_add3_u32 v43, v42, v43, s43
	v_lshrrev_b32_e32 v216, 16, v43
	v_fmamk_f32 v43, v56, 0xbfb8aa3b, v82
	v_exp_f32_e32 v43, v43
	v_mov_b32_e32 v55, v46
	v_add_f32_e32 v43, 1.0, v43
	v_rcp_f32_e32 v43, v43
	s_nop 0
	v_mul_f32_e32 v43, v84, v43
	v_exp_f32_e32 v51, v43
	s_nop 0
	v_fma_f32 v43, -v51, v51, 1.0
	v_max_f32_e32 v43, 0, v43
	v_sqrt_f32_e32 v43, v43
	s_nop 0
	v_mul_f32_e32 v54, v44, v43
	v_mul_f32_e32 v44, v51, v46
	v_pk_fma_f32 v[46:47], v[50:51], v[54:55], v[44:45] op_sel_hi:[1,1,0]
	v_fmamk_f32 v44, v53, 0xbfb8aa3b, v80
	v_bfe_u32 v43, v46, 16, 1
	v_add3_u32 v43, v46, v43, s43
	v_and_or_b32 v216, v43, s100, v216
	v_fmamk_f32 v43, v49, 0xbfb8aa3b, v67
	v_exp_f32_e32 v43, v43
	v_exp_f32_e32 v44, v44
	v_mov_b32_e32 v45, v42
	v_add_f32_e32 v43, 1.0, v43
	v_rcp_f32_e32 v43, v43
	v_add_f32_e32 v44, 1.0, v44
	v_rcp_f32_e32 v44, v44
	v_mul_f32_e32 v43, v81, v43
	v_exp_f32_e32 v49, v43
	s_nop 0
	v_fma_f32 v43, -v49, v49, 1.0
	v_max_f32_e32 v43, 0, v43
	v_sqrt_f32_e32 v43, v43
	s_nop 0
	v_mul_f32_e32 v44, v44, v43
	v_pk_mul_f32 v[42:43], v[48:49], v[44:45]
	v_fmamk_f32 v44, v57, 0xbfb8aa3b, v82
	v_exp_f32_e32 v44, v44
	v_fmamk_f32 v45, v61, 0xbfb8aa3b, v83
	v_exp_f32_e32 v45, v45
	v_mov_b32_e32 v49, v46
	v_add_f32_e32 v44, 1.0, v44
	v_rcp_f32_e32 v44, v44
	v_add_f32_e32 v45, 1.0, v45
	v_rcp_f32_e32 v47, v45
	v_mov_b32_e32 v46, v42
	v_mul_f32_e32 v44, v84, v44
	v_exp_f32_e32 v45, v44
	s_nop 0
	v_fma_f32 v44, -v45, v45, 1.0
	v_max_f32_e32 v44, 0, v44
	v_sqrt_f32_e32 v44, v44
	s_nop 0
	v_mul_f32_e32 v48, v47, v44
	v_mov_b32_e32 v44, v65
	v_pk_mul_f32 v[44:45], v[44:45], v[48:49]
	s_nop 0
	v_mov_b32_e32 v47, v44
	v_mov_b32_e32 v44, v43
	v_pk_add_f32 v[76:77], v[46:47], v[44:45]
	s_nop 0
	v_bfe_u32 v42, v76, 16, 1
	v_add3_u32 v42, v76, v42, s43
	v_lshrrev_b32_e32 v217, 16, v42
	v_bfe_u32 v42, v77, 16, 1
	v_add3_u32 v42, v77, v42, s43
	v_and_or_b32 v217, v42, s100, v217
	global_store_dwordx4 v[212:213], v[214:217], off
	s_cbranch_scc1 .LBB0_714
; template <int MODE, int DIR> __device__ __forceinline__ void lru_dir(const Args& a, int l, int lane, int tok0, int nb, int half, const LAS unsigned char* xt, bf16* hf) {
;     ...
;     pg8::bf16x8 wa[2][2], wx[2][2];
;     { const pg8::bf16x8* wp = (const pg8::bf16x8*)(a.ws + WS_TWF) + (size_t)((DIR * 8 + nb) * 2) * 4 * 2 * 64 + lane;
; #pragma unroll
;       for (int c2 = 0; c2 < 2; ++c2)
; #pragma unroll
;           for (int ks = 0; ks < 2; ++ks) { wa[c2][ks] = wp[((2 * half + c2) * 2 + ks) * 64]; wx[c2][ks] = wp[(8 + (2 * half + c2) * 2 + ks) * 64]; } }
;     pg8::bf16x8 idn[2];
; #pragma unroll
;     for (int hf = 0; hf < 2; ++hf) { v4u w;
; #pragma unroll
;         for (int jj = 0; jj < 4; ++jj) { const int k0 = 8 * g + 2 * jj; w[jj] = ((k0 == 16 * hf + n) ? 0x3f80u : 0u) | ((k0 + 1 == 16 * hf + n) ? 0x3f800000u : 0u); }
;         idn[hf] = __builtin_bit_cast(pg8::bf16x8, w); }
;     float ba[2], bx[2], ls8[2], h[2], P[2];
;     const int cch = 64 * nb + 32 * half + n;
; #pragma unroll
;     for (int c2 = 0; c2 < 2; ++c2) { const int c = cch + 16 * c2; const size_t ix = (size_t)(l * 2 + DIR) * 512 + c;
;         ba[c2] = -1.4426950408889634f * a.in[I_LBA][ix]; bx[c2] = -1.4426950408889634f * a.in[I_LBX][ix]; ls8[c2] = (-8.f * 1.4426950408889634f) * log1pf(__expf(-a.in[I_LAM][ix]));
;         h[c2] = MODE ? cin[((size_t)ch * 2 + DIR) * 512 + c] : 0.f; P[c2] = 1.f; }
	v_readlane_b32 s4, v252, 51
	s_add_u32 s62, s4, s38
	v_readlane_b32 s4, v252, 52
	s_addc_u32 s63, s4, s39
	s_lshl_b32 s1, s1, 4
	s_add_u32 s4, s90, s1
	s_addc_u32 s5, s91, 0
	v_lshlrev_b32_e32 v190, 4, v126
	v_lshl_add_u64 v[10:11], s[4:5], 0, v[190:191]
	s_lshl_b32 s82, s0, 4
	v_lshl_add_u64 v[14:15], v[10:11], 0, s[82:83]
	s_mov_b64 s[0:1], 0x5f20000
	v_lshl_add_u64 v[34:35], v[14:15], 0, s[0:1]
	s_mov_b32 s0, 0x5f20000
	v_add_co_u32_e32 v10, vcc, s0, v14
	s_mov_b32 s0, 0x5f22000
	s_nop 0
	v_addc_co_u32_e32 v11, vcc, 0, v15, vcc
	v_add_co_u32_e32 v38, vcc, s0, v14
	global_load_dwordx4 v[10:13], v[10:11], off
	s_nop 0
	v_addc_co_u32_e32 v39, vcc, 0, v15, vcc
	global_load_dwordx4 v[14:17], v[38:39], off
	global_load_dwordx4 v[18:21], v[34:35], off offset:1024
	global_load_dwordx4 v[22:25], v[38:39], off offset:1024
	global_load_dwordx4 v[26:29], v[34:35], off offset:2048
	global_load_dwordx4 v[30:33], v[38:39], off offset:2048
	s_nop 0
	global_load_dwordx4 v[34:37], v[34:35], off offset:3072
	s_nop 0
	global_load_dwordx4 v[38:41], v[38:39], off offset:3072
	v_readlane_b32 s0, v252, 53
	global_load_dword v44, v[72:73], off offset:2048
	v_readlane_b32 s1, v252, 54
	s_mov_b32 s20, 0x7f800000
	s_mov_b32 s21, 0x33800000
	v_lshl_add_u64 v[42:43], s[0:1], 0, v[68:69]
	s_mov_b32 s0, 0x3f2aaaab
	s_mov_b32 s1, 0x3f317218
	v_lshlrev_b32_e32 v190, 2, v66
	v_lshl_add_u64 v[42:43], v[42:43], 0, v[190:191]
	v_add_u32_e32 v190, s59, v66
	v_readlane_b32 s4, v250, 28
	v_readlane_b32 s5, v250, 29
	v_readlane_b32 s8, v250, 32
	v_readlane_b32 s9, v250, 33
	v_readlane_b32 s10, v250, 34
	v_readlane_b32 s11, v250, 35
	global_load_dword v68, v[42:43], off
	v_readlane_b32 s6, v250, 30
	v_readlane_b32 s7, v250, 31
	v_readlane_b32 s12, v250, 36
	v_readlane_b32 s13, v250, 37
	v_readlane_b32 s14, v250, 38
	v_readlane_b32 s15, v250, 39
	v_readlane_b32 s16, v250, 40
	v_readlane_b32 s17, v250, 41
	v_readlane_b32 s18, v250, 42
	v_readlane_b32 s19, v250, 43
	s_waitcnt vmcnt(1)
	v_mul_f32_e32 v78, 0xbfb8aa3b, v44
	global_load_dword v44, v[74:75], off offset:2048
	s_waitcnt vmcnt(0)
	v_mul_f32_e32 v79, 0xbfb8aa3b, v44
	global_load_dword v44, v[70:71], off offset:2048
	global_load_dword v74, v[42:43], off offset:64
	v_or_b32_e32 v42, s66, v156
	v_ashrrev_i32_e32 v43, 31, v42
	v_lshl_add_u64 v[70:71], v[132:133], 0, s[38:39]
	s_waitcnt vmcnt(1)
	v_mul_f32_e32 v44, 0xbfb8aa3b, v44
	v_exp_f32_e32 v46, v44
	s_nop 0
	v_add_f32_e32 v47, 1.0, v46
	v_add_f32_e32 v44, -1.0, v47
	v_sub_f32_e32 v45, v44, v47
	v_add_f32_e32 v45, 1.0, v45
	v_sub_f32_e32 v44, v46, v44
	v_add_f32_e32 v48, v44, v45
	v_frexp_mant_f32_e32 v44, v47
	v_cmp_gt_f32_e32 vcc, s0, v44
	v_cvt_f64_f32_e32 v[44:45], v47
	v_frexp_exp_i32_f64_e32 v44, v[44:45]
	v_subbrev_co_u32_e32 v44, vcc, 0, v44, vcc
	v_sub_u32_e32 v45, 0, v44
	v_ldexp_f32 v47, v47, v45
	v_ldexp_f32 v45, v48, v45
	v_add_f32_e32 v48, -1.0, v47
	v_add_f32_e32 v49, 1.0, v48
	v_sub_f32_e32 v49, v47, v49
	v_add_f32_e32 v49, v45, v49
	v_add_f32_e32 v50, v48, v49
	v_sub_f32_e32 v48, v50, v48
	v_sub_f32_e32 v48, v49, v48
	v_add_f32_e32 v49, 1.0, v47
	v_add_f32_e32 v51, -1.0, v49
	v_sub_f32_e32 v47, v47, v51
	v_add_f32_e32 v45, v45, v47
	v_add_f32_e32 v47, v49, v45
	v_sub_f32_e32 v49, v47, v49
	v_sub_f32_e32 v45, v45, v49
	v_rcp_f32_e32 v49, v47
	v_cvt_f32_i32_e32 v44, v44
	v_cmp_neq_f32_e32 vcc, s20, v46
	v_mul_f32_e32 v51, v50, v49
	v_mul_f32_e32 v52, v47, v51
	v_fma_f32 v53, v51, v47, -v52
	v_fmac_f32_e32 v53, v51, v45
	v_add_f32_e32 v54, v52, v53
	v_sub_f32_e32 v55, v50, v54
	v_sub_f32_e32 v50, v50, v55
	v_sub_f32_e32 v52, v54, v52
	v_sub_f32_e32 v50, v50, v54
	v_add_f32_e32 v48, v48, v50
	v_sub_f32_e32 v50, v52, v53
	v_add_f32_e32 v48, v50, v48
	v_add_f32_e32 v50, v55, v48
	v_mul_f32_e32 v52, v49, v50
	v_mul_f32_e32 v53, v47, v52
	v_fma_f32 v47, v52, v47, -v53
	v_fmac_f32_e32 v47, v52, v45
	v_sub_f32_e32 v45, v55, v50
	v_add_f32_e32 v45, v48, v45
	v_add_f32_e32 v48, v53, v47
	v_sub_f32_e32 v54, v50, v48
	v_sub_f32_e32 v50, v50, v54
	v_sub_f32_e32 v53, v48, v53
	v_sub_f32_e32 v48, v50, v48
	v_add_f32_e32 v45, v45, v48
	v_sub_f32_e32 v47, v53, v47
	v_add_f32_e32 v45, v47, v45
	v_add_f32_e32 v47, v51, v52
	v_add_f32_e32 v45, v54, v45
	v_sub_f32_e32 v48, v47, v51
	v_mul_f32_e32 v45, v49, v45
	v_sub_f32_e32 v48, v52, v48
	v_add_f32_e32 v45, v48, v45
	v_mul_f32_e32 v51, 0x3f317218, v44
	v_add_f32_e32 v48, v47, v45
	v_fma_f32 v52, v44, s1, -v51
	v_mul_f32_e32 v49, v48, v48
	v_fmac_f32_e32 v52, 0xb102e308, v44
	v_sub_f32_e32 v44, v48, v47
	v_fmamk_f32 v50, v49, 0x3e9b6dac, v228
	v_sub_f32_e32 v44, v45, v44
	v_add_f32_e32 v45, v51, v52
	v_fmaak_f32 v50, v49, v50, 0x3f2aaada
	v_sub_f32_e32 v47, v45, v51
	v_ldexp_f32 v51, v48, 1
	v_mul_f32_e32 v48, v48, v49
	v_mul_f32_e32 v48, v48, v50
	v_add_f32_e32 v49, v51, v48
	v_sub_f32_e32 v50, v49, v51
	v_ldexp_f32 v44, v44, 1
	v_sub_f32_e32 v48, v48, v50
	v_add_f32_e32 v44, v44, v48
	v_add_f32_e32 v48, v49, v44
	v_sub_f32_e32 v49, v48, v49
	v_sub_f32_e32 v44, v44, v49
	v_add_f32_e32 v49, v45, v48
	v_sub_f32_e32 v50, v49, v45
	v_sub_f32_e32 v51, v49, v50
	v_sub_f32_e32 v47, v52, v47
	v_sub_f32_e32 v45, v45, v51
	v_sub_f32_e32 v48, v48, v50
	v_add_f32_e32 v45, v48, v45
	v_add_f32_e32 v48, v47, v44
	v_sub_f32_e32 v50, v48, v47
	v_sub_f32_e32 v51, v48, v50
	v_sub_f32_e32 v47, v47, v51
	v_sub_f32_e32 v44, v44, v50
	v_add_f32_e32 v45, v48, v45
	v_add_f32_e32 v44, v44, v47
	v_add_f32_e32 v47, v49, v45
	v_sub_f32_e32 v48, v47, v49
	v_sub_f32_e32 v45, v45, v48
	v_add_f32_e32 v44, v44, v45
	v_add_f32_e32 v44, v47, v44
	v_cndmask_b32_e32 v44, v231, v44, vcc
	v_cmp_ngt_f32_e32 vcc, -1.0, v46
	s_nop 1
	v_cndmask_b32_e32 v44, v232, v44, vcc
	v_cmp_neq_f32_e32 vcc, -1.0, v46
	s_nop 1
	v_cndmask_b32_e32 v44, v233, v44, vcc
	v_cmp_lt_f32_e64 vcc, |v46|, s21
	s_nop 1
	v_cndmask_b32_e32 v44, v44, v46, vcc
	v_mul_f32_e32 v80, 0xc138aa3b, v44
	v_lshlrev_b64 v[44:45], 2, v[190:191]
	v_lshl_add_u64 v[46:47], s[4:5], 0, v[44:45]
	global_load_dword v46, v[46:47], off offset:64
	v_lshlrev_b32_e32 v190, 1, v66
	s_waitcnt vmcnt(0)
; #define LAS __attribute__((address_space(3)))
; #define VM_WAIT() asm volatile("s_waitcnt vmcnt(0)" ::: "memory")
; template <int MODE, int DIR> __device__ __forceinline__ void lru_dir(const Args& a, int l, int lane, int tok0, int nb, int half, const LAS unsigned char* xt, bf16* hf) {
;     ...
;     for (int c2 = 0; c2 < 2; ++c2) { const int c = cch + 16 * c2; const size_t ix = (size_t)(l * 2 + DIR) * 512 + c;
;         ba[c2] = -1.4426950408889634f * a.in[I_LBA][ix]; bx[c2] = -1.4426950408889634f * a.in[I_LBX][ix]; ls8[c2] = (-8.f * 1.4426950408889634f) * log1pf(__expf(-a.in[I_LAM][ix]));
;         h[c2] = MODE ? cin[((size_t)ch * 2 + DIR) * 512 + c] : 0.f; P[c2] = 1.f; }
;     const LAS unsigned char* xa = xt + ((n >> 2) * LCH + (n & 3)) * 128 + g * 16;
;     bf16* yo = Y + (size_t)(tok0 + g * LCH) * DM + 1024 + cch;
;     const bf16* go = Z + (size_t)(tok0 + g * LCH) * ZRW + RGT + cch;
;     constexpr int NST = LCH / 4, T0 = DIR ? (LCH - 4) : 0, DT = DIR ? -4 : 4;
;     unsigned short yn[2][4], gn[2][4];
;     if (MODE && DIR) {
;         VM_WAIT();
; #pragma unroll
;         for (int rg = 0; rg < 4; ++rg)
; #pragma unroll
;             for (int c2 = 0; c2 < 2; ++c2) { yn[c2][rg] = hf[(((T0 >> 2) * 4 + rg) * 2 + c2) * 64 + lane]; gn[c2][rg] = go[(size_t)(T0 + rg) * ZRW + 16 * c2]; } }
	v_mul_f32_e32 v81, 0xbfb8aa3b, v46
	v_lshl_add_u64 v[46:47], s[8:9], 0, v[44:45]
	v_lshl_add_u64 v[44:45], s[10:11], 0, v[44:45]
	global_load_dword v44, v[44:45], off offset:64
	s_waitcnt vmcnt(0)
	v_mul_f32_e32 v44, 0xbfb8aa3b, v44
	global_load_dword v46, v[46:47], off offset:64
	s_waitcnt vmcnt(0)
	s_waitcnt vmcnt(0)
	v_mul_f32_e32 v82, 0xbfb8aa3b, v46
	v_exp_f32_e32 v46, v44
	s_nop 0
	v_add_f32_e32 v47, 1.0, v46
	v_add_f32_e32 v44, -1.0, v47
	v_sub_f32_e32 v45, v44, v47
	v_add_f32_e32 v45, 1.0, v45
	v_sub_f32_e32 v44, v46, v44
	v_add_f32_e32 v48, v44, v45
	v_frexp_mant_f32_e32 v44, v47
	v_cmp_gt_f32_e32 vcc, s0, v44
	v_cvt_f64_f32_e32 v[44:45], v47
	v_frexp_exp_i32_f64_e32 v44, v[44:45]
	v_subbrev_co_u32_e32 v44, vcc, 0, v44, vcc
	v_sub_u32_e32 v45, 0, v44
	v_ldexp_f32 v47, v47, v45
	v_ldexp_f32 v45, v48, v45
	v_add_f32_e32 v48, -1.0, v47
	v_add_f32_e32 v49, 1.0, v48
	v_sub_f32_e32 v49, v47, v49
	v_add_f32_e32 v49, v45, v49
	v_add_f32_e32 v50, v48, v49
	v_sub_f32_e32 v48, v50, v48
	v_sub_f32_e32 v48, v49, v48
	v_add_f32_e32 v49, 1.0, v47
	v_add_f32_e32 v51, -1.0, v49
	v_sub_f32_e32 v47, v47, v51
	v_add_f32_e32 v45, v45, v47
	v_add_f32_e32 v47, v49, v45
	v_sub_f32_e32 v49, v47, v49
	v_sub_f32_e32 v45, v45, v49
	v_rcp_f32_e32 v49, v47
	v_cvt_f32_i32_e32 v44, v44
	v_cmp_neq_f32_e32 vcc, s20, v46
	s_movk_i32 s0, 0x1000
	v_mul_f32_e32 v51, v50, v49
	v_mul_f32_e32 v52, v47, v51
	v_fma_f32 v53, v51, v47, -v52
	v_fmac_f32_e32 v53, v51, v45
	v_add_f32_e32 v54, v52, v53
	v_sub_f32_e32 v55, v50, v54
	v_sub_f32_e32 v50, v50, v55
	v_sub_f32_e32 v52, v54, v52
	v_sub_f32_e32 v50, v50, v54
	v_add_f32_e32 v48, v48, v50
	v_sub_f32_e32 v50, v52, v53
	v_add_f32_e32 v48, v50, v48
	v_add_f32_e32 v50, v55, v48
	v_mul_f32_e32 v52, v49, v50
	v_mul_f32_e32 v53, v47, v52
	v_fma_f32 v47, v52, v47, -v53
	v_fmac_f32_e32 v47, v52, v45
	v_sub_f32_e32 v45, v55, v50
	v_add_f32_e32 v45, v48, v45
	v_add_f32_e32 v48, v53, v47
	v_sub_f32_e32 v54, v50, v48
	v_sub_f32_e32 v50, v50, v54
	v_sub_f32_e32 v53, v48, v53
	v_sub_f32_e32 v48, v50, v48
	v_add_f32_e32 v45, v45, v48
	v_sub_f32_e32 v47, v53, v47
	v_add_f32_e32 v45, v47, v45
	v_add_f32_e32 v47, v51, v52
	v_add_f32_e32 v45, v54, v45
	v_sub_f32_e32 v48, v47, v51
	v_mul_f32_e32 v45, v49, v45
	v_sub_f32_e32 v48, v52, v48
	v_add_f32_e32 v45, v48, v45
	v_mul_f32_e32 v51, 0x3f317218, v44
	v_add_f32_e32 v48, v47, v45
	v_fma_f32 v52, v44, s1, -v51
	v_mul_f32_e32 v49, v48, v48
	v_fmac_f32_e32 v52, 0xb102e308, v44
	v_sub_f32_e32 v44, v48, v47
	v_fmamk_f32 v50, v49, 0x3e9b6dac, v228
	v_sub_f32_e32 v44, v45, v44
	v_add_f32_e32 v45, v51, v52
	v_fmaak_f32 v50, v49, v50, 0x3f2aaada
	v_sub_f32_e32 v47, v45, v51
	v_ldexp_f32 v51, v48, 1
	v_mul_f32_e32 v48, v48, v49
	v_mul_f32_e32 v48, v48, v50
	v_add_f32_e32 v49, v51, v48
	v_sub_f32_e32 v50, v49, v51
	v_ldexp_f32 v44, v44, 1
	v_sub_f32_e32 v48, v48, v50
	v_add_f32_e32 v44, v44, v48
	v_add_f32_e32 v48, v49, v44
	v_sub_f32_e32 v49, v48, v49
	v_sub_f32_e32 v44, v44, v49
	v_add_f32_e32 v49, v45, v48
	v_sub_f32_e32 v50, v49, v45
	v_sub_f32_e32 v51, v49, v50
	v_sub_f32_e32 v47, v52, v47
	v_sub_f32_e32 v45, v45, v51
	v_sub_f32_e32 v48, v48, v50
	v_add_f32_e32 v45, v48, v45
	v_add_f32_e32 v48, v47, v44
	v_sub_f32_e32 v50, v48, v47
	v_sub_f32_e32 v51, v48, v50
	v_sub_f32_e32 v47, v47, v51
	v_sub_f32_e32 v44, v44, v50
	v_add_f32_e32 v45, v48, v45
	v_add_f32_e32 v44, v44, v47
	v_add_f32_e32 v47, v49, v45
	v_sub_f32_e32 v48, v47, v49
	v_sub_f32_e32 v45, v45, v48
	v_add_f32_e32 v44, v44, v45
	v_add_f32_e32 v44, v47, v44
	v_cndmask_b32_e32 v44, v231, v44, vcc
	v_cmp_ngt_f32_e32 vcc, -1.0, v46
	s_nop 1
	v_cndmask_b32_e32 v44, v232, v44, vcc
	v_cmp_neq_f32_e32 vcc, -1.0, v46
	s_nop 1
	v_cndmask_b32_e32 v44, v233, v44, vcc
	v_cmp_lt_f32_e64 vcc, |v46|, s21
	s_nop 1
	v_cndmask_b32_e32 v44, v44, v46, vcc
	v_mul_f32_e32 v83, 0xc138aa3b, v44
	v_lshlrev_b64 v[44:45], 12, v[42:43]
	v_lshlrev_b64 v[42:43], 10, v[42:43]
	v_sub_co_u32_e32 v42, vcc, 0, v42
	v_lshl_add_u64 v[44:45], s[90:91], 0, v[44:45]
	s_nop 0
	v_subb_co_u32_e32 v43, vcc, 0, v43, vcc
	v_lshl_add_u64 v[42:43], v[44:45], 0, v[42:43]
	v_lshlrev_b32_e32 v44, 1, v126
	v_mov_b32_e32 v45, v191
	v_lshl_add_u64 v[44:45], s[62:63], 0, v[44:45]
	v_add_co_u32_e32 v44, vcc, s0, v44
	v_lshl_add_u64 v[42:43], v[42:43], 0, v[190:191]
	s_nop 0
	v_addc_co_u32_e32 v45, vcc, 0, v45, vcc
	s_mov_b32 s0, 0x1f015000
	v_add_co_u32_e32 v46, vcc, s0, v42
	s_mov_b32 s0, 0x1f016000
	s_nop 0
	v_addc_co_u32_e32 v47, vcc, 0, v43, vcc
	v_lshl_add_u64 v[212:213], v[44:45], 0, v[210:211]
	global_load_dwordx4 v[214:217], v[212:213], off offset:3072
	global_load_ushort v86, v[46:47], off offset:1024
	global_load_ushort v84, v[46:47], off offset:1056
	v_add_co_u32_e32 v46, vcc, s0, v42
	s_mov_b32 s0, 0x1f017000
	s_nop 0
	v_addc_co_u32_e32 v47, vcc, 0, v43, vcc
	v_add_co_u32_e32 v42, vcc, s0, v42
	global_load_ushort v104, v[46:47], off
	global_load_ushort v88, v[46:47], off offset:32
	global_load_ushort v110, v[46:47], off offset:3072
	global_load_ushort v108, v[46:47], off offset:3104
	v_addc_co_u32_e32 v43, vcc, 0, v43, vcc
	global_load_ushort v75, v[42:43], off offset:2048
	global_load_ushort v112, v[42:43], off offset:2080
	v_add_u32_e32 v42, s66, v156
	v_ashrrev_i32_e32 v43, 31, v42
	v_mad_i64_i32 v[66:67], s[0:1], v42, s30, 0
	v_lshlrev_b64 v[72:73], 12, v[42:43]
	v_or_b32_e32 v66, v66, v190
	v_or_b32_e32 v72, v72, v190
	s_movk_i32 s0, 0xe00
	s_waitcnt vmcnt(0)
	v_mov_b32_e32 v87, v214
	v_lshrrev_b32_e32 v85, 16, v214
	v_mov_b32_e32 v105, v215
	v_lshrrev_b32_e32 v89, 16, v215
	v_mov_b32_e32 v111, v216
	v_lshrrev_b32_e32 v109, 16, v216
	v_mov_b32_e32 v76, v217
	v_lshrrev_b32_e32 v113, 16, v217
	v_mov_b32_e32 v218, v214
	v_mov_b32_e32 v219, v215
	v_mov_b32_e32 v220, v216
	v_mov_b32_e32 v221, v217
	v_mov_b32_e32 v91, v86
	s_waitcnt vmcnt(13)
	v_mov_b32_e32 v94, v85
	s_waitcnt vmcnt(12)
	v_mov_b32_e32 v92, v84
	v_mov_b32_e32 v90, v87
	s_waitcnt vmcnt(10)
	v_mov_b32_e32 v95, v104
	v_mov_b32_e32 v93, v105
	s_waitcnt vmcnt(8)
	v_mov_b32_e32 v97, v88
	s_waitcnt vmcnt(7)
	v_mov_b32_e32 v99, v111
	s_waitcnt vmcnt(6)
	v_mov_b32_e32 v96, v110
	v_mov_b32_e32 v100, v89
	s_waitcnt vmcnt(4)
	v_mov_b32_e32 v98, v108
	s_waitcnt vmcnt(3)
	v_mov_b32_e32 v101, v76
	s_waitcnt vmcnt(2)
	v_mov_b32_e32 v103, v75
	v_mov_b32_e32 v102, v109
	s_waitcnt vmcnt(0)
	v_mov_b32_e32 v107, v112
	v_mov_b32_e32 v106, v113
	s_branch .LBB0_717
; #define LAS __attribute__((address_space(3)))
; template <int MODE, int DIR> __device__ __forceinline__ void lru_dir(const Args& a, int l, int lane, int tok0, int nb, int half, const LAS unsigned char* xt, bf16* hf) {
;     ...
;     for (int step = 0; step < NST; ++step) {
;         const int t4 = T0 + DT * step;
;         unsigned short yc[2][4], gc[2][4];
;         if (MODE && DIR) {
; #pragma unroll
;             for (int rg = 0; rg < 4; ++rg)
; #pragma unroll
;                 for (int c2 = 0; c2 < 2; ++c2) { yc[c2][rg] = yn[c2][rg]; gc[c2][rg] = gn[c2][rg]; }
;             if (step + 1 < NST) {
; #pragma unroll
;                 for (int rg = 0; rg < 4; ++rg)
; #pragma unroll
;                     for (int c2 = 0; c2 < 2; ++c2) { yn[c2][rg] = hf[((((t4 + DT) >> 2) * 4 + rg) * 2 + c2) * 64 + lane]; gn[c2][rg] = go[(size_t)(t4 + DT + rg) * ZRW + 16 * c2]; } } }
;         const pg8::bf16x8 a0 = *(const LAS pg8::bf16x8*)(xa + t4 * 128), a1 = *(const LAS pg8::bf16x8*)(xa + t4 * 128 + 64);
;         const pg8::bf16x8 ah = half ? a1 : a0;
;         f32x4 pa[2], px[2], xd[2];
; #pragma unroll
;         for (int c2 = 0; c2 < 2; ++c2) { const f32x4 z4 = (f32x4){0.f, 0.f, 0.f, 0.f};
;             pa[c2] = __builtin_amdgcn_mfma_f32_16x16x32_bf16(a0, wa[c2][0], z4, 0, 0, 0); pa[c2] = __builtin_amdgcn_mfma_f32_16x16x32_bf16(a1, wa[c2][1], pa[c2], 0, 0, 0);
;             px[c2] = __builtin_amdgcn_mfma_f32_16x16x32_bf16(a0, wx[c2][0], z4, 0, 0, 0); px[c2] = __builtin_amdgcn_mfma_f32_16x16x32_bf16(a1, wx[c2][1], px[c2], 0, 0, 0);
;             xd[c2] = __builtin_amdgcn_mfma_f32_16x16x32_bf16(ah, idn[c2], z4, 0, 0, 0); }
; #pragma unroll
;         for (int rr = 0; rr < 4; ++rr) { const int rg = DIR ? 3 - rr : rr;
; #pragma unroll
;             for (int c2 = 0; c2 < 2; ++c2) {
;                 const float r_ = frcp(1.f + __builtin_amdgcn_exp2f(__builtin_fmaf(pa[c2][rg], -1.4426950408889634f, ba[c2]))), i_ = frcp(1.f + __builtin_amdgcn_exp2f(__builtin_fmaf(px[c2][rg], -1.4426950408889634f, bx[c2])));
;                 const float av = __builtin_amdgcn_exp2f(ls8[c2] * r_), mult = fsqrt_(fmaxf(1.f - av * av, 0.f));
;                 h[c2] = av * h[c2] + mult * i_ * xd[c2][rg]; P[c2] *= av;
;                 if (MODE) {
;                     if (DIR == 0) hf[(((t4 >> 2) * 4 + rg) * 2 + c2) * 64 + lane] = (bf16)f2bf(h[c2]);
.LBB0_716:
	v_add_u32_e32 v46, s0, v157
	ds_read_b128 v[42:45], v46
	ds_read_b128 v[46:49], v46 offset:64
	s_mov_b32 s1, 0x2681f000
	s_movk_i32 s4, 0xfc00
	s_mov_b32 s5, -1
	s_waitcnt lgkmcnt(1)
	v_mfma_f32_16x16x32_bf16 v[50:53], v[42:45], v[10:13], 0
	s_waitcnt lgkmcnt(0)
	v_cndmask_b32_e64 v117, v49, v45, s[92:93]
	v_cndmask_b32_e64 v116, v48, v44, s[92:93]
	v_cndmask_b32_e64 v115, v47, v43, s[92:93]
	v_mfma_f32_16x16x32_bf16 v[62:65], v[46:49], v[18:21], v[50:53]
	v_cndmask_b32_e64 v114, v46, v42, s[92:93]
	v_lshl_add_u64 v[70:71], v[70:71], 0, s[4:5]
	s_movk_i32 s4, 0xc000
	v_mfma_f32_16x16x32_bf16 v[50:53], v[42:45], v[14:17], 0
	s_addk_i32 s0, 0xfe00
	s_nop 2
	v_fmamk_f32 v65, v65, 0xbfb8aa3b, v78
	v_exp_f32_e32 v65, v65
	v_mfma_f32_16x16x32_bf16 v[58:61], v[46:49], v[22:25], v[50:53]
	s_mov_b32 s5, -1
	v_lshl_add_u64 v[66:67], v[66:67], 0, s[40:41]
	v_add_f32_e32 v65, 1.0, v65
	v_rcp_f32_e32 v65, v65
	v_mfma_f32_16x16x32_bf16 v[50:53], v[42:45], v[26:29], 0
	s_nop 2
	v_fmamk_f32 v61, v61, 0xbfb8aa3b, v79
	v_exp_f32_e32 v61, v61
	v_mul_f32_e32 v65, v80, v65
	v_mfma_f32_16x16x32_bf16 v[42:45], v[42:45], v[30:33], 0
	s_cmpk_eq_i32 s0, 0xfe00
	v_add_f32_e32 v61, 1.0, v61
	v_rcp_f32_e32 v61, v61
	v_mfma_f32_16x16x32_bf16 v[54:57], v[114:117], v[2:5], 0
	v_mfma_f32_16x16x32_bf16 v[50:53], v[46:49], v[34:37], v[50:53]
	v_mfma_f32_16x16x32_bf16 v[46:49], v[46:49], v[38:41], v[42:45]
	s_nop 5
	v_mov_b32_e32 v69, v57
	v_fmamk_f32 v53, v53, 0xbfb8aa3b, v81
	v_exp_f32_e32 v53, v53
	v_mfma_f32_16x16x32_bf16 v[42:45], v[114:117], v[6:9], 0
	v_exp_f32_e32 v114, v65
	v_fmamk_f32 v49, v49, 0xbfb8aa3b, v82
	v_add_f32_e32 v53, 1.0, v53
	v_rcp_f32_e32 v53, v53
	v_fma_f32 v65, -v114, v114, 1.0
	v_max_f32_e32 v65, 0, v65
	v_sqrt_f32_e32 v65, v65
	v_mul_f32_e32 v53, v83, v53
	v_exp_f32_e32 v49, v49
	v_fmamk_f32 v48, v48, 0xbfb8aa3b, v82
	v_mul_f32_e32 v115, v61, v65
	v_mul_f32_e32 v116, v57, v115
	v_lshlrev_b32_e32 v61, 16, v75
	v_pk_fma_f32 v[68:69], v[68:69], v[114:115], v[116:117] op_sel_hi:[1,1,0]
	v_mul_f32_e32 v65, v61, v61
	v_mul_f32_e32 v69, 0x40135761, v61
	v_fma_f32 v65, v65, s58, 1.0
	v_mul_f32_e32 v65, v69, v65
	v_exp_f32_e32 v65, v65
	v_exp_f32_e32 v116, v53
	v_add_f32_e32 v49, 1.0, v49
	v_rcp_f32_e32 v49, v49
	v_add_f32_e32 v65, 1.0, v65
	v_rcp_f32_e32 v65, v65
	v_fma_f32 v53, -v116, v116, 1.0
	v_max_f32_e32 v53, 0, v53
	v_sqrt_f32_e32 v53, v53
	v_lshlrev_b32_e32 v57, 16, v76
	v_add_f32_e32 v57, v68, v57
	v_fma_f32 v61, -v65, v61, v61
	v_mul_f32_e32 v57, v61, v57
	v_lshl_add_u64 v[76:77], s[90:91], 0, v[72:73]
	v_bfe_u32 v61, v57, 16, 1
	v_add_co_u32_e32 v114, vcc, s1, v76
	v_mul_f32_e32 v117, v49, v53
	v_lshlrev_b32_e32 v49, 16, v112
	v_add3_u32 v57, v57, v61, s43
	v_addc_co_u32_e32 v115, vcc, 0, v77, vcc
	v_mul_f32_e32 v53, v49, v49
	global_store_short_d16_hi v[114:115], v57, off offset:2048
	v_mul_f32_e32 v57, 0x40135761, v49
	v_fma_f32 v53, v53, s58, 1.0
	v_mul_f32_e32 v53, v57, v53
	v_exp_f32_e32 v53, v53
	v_mov_b32_e32 v75, v45
	v_mul_f32_e32 v118, v45, v117
	v_pk_fma_f32 v[74:75], v[74:75], v[116:117], v[118:119] op_sel_hi:[1,1,0]
	v_add_f32_e32 v53, 1.0, v53
	v_rcp_f32_e32 v53, v53
	v_lshlrev_b32_e32 v45, 16, v113
	v_add_f32_e32 v45, v74, v45
	v_mov_b32_e32 v61, v68
	v_fma_f32 v49, -v53, v49, v49
	v_mul_f32_e32 v45, v49, v45
	v_bfe_u32 v49, v45, 16, 1
	v_add3_u32 v45, v45, v49, s43
	global_store_short_d16_hi v[114:115], v45, off offset:2080
	v_fmamk_f32 v45, v64, 0xbfb8aa3b, v78
	v_exp_f32_e32 v45, v45
	v_fmamk_f32 v49, v60, 0xbfb8aa3b, v79
	v_exp_f32_e32 v49, v49
	s_mov_b32 s1, 0x2681e000
	v_add_f32_e32 v45, 1.0, v45
	v_rcp_f32_e32 v45, v45
	v_add_f32_e32 v49, 1.0, v49
	v_rcp_f32_e32 v49, v49
	v_exp_f32_e32 v48, v48
	v_mul_f32_e32 v45, v80, v45
	v_exp_f32_e32 v57, v45
	v_fmamk_f32 v47, v47, 0xbfb8aa3b, v82
	v_add_f32_e32 v48, 1.0, v48
	v_rcp_f32_e32 v48, v48
	v_fma_f32 v45, -v57, v57, 1.0
	v_max_f32_e32 v45, 0, v45
	v_sqrt_f32_e32 v45, v45
	v_mul_f32_e32 v64, v57, v68
	v_exp_f32_e32 v47, v47
	v_fmamk_f32 v46, v46, 0xbfb8aa3b, v82
	v_mul_f32_e32 v60, v49, v45
	v_lshlrev_b32_e32 v49, 16, v110
	v_pk_fma_f32 v[56:57], v[56:57], v[60:61], v[64:65] op_sel_hi:[1,1,0]
	v_mul_f32_e32 v53, v49, v49
	v_mul_f32_e32 v57, 0x40135761, v49
	v_fma_f32 v53, v53, s58, 1.0
	v_mul_f32_e32 v53, v57, v53
	v_exp_f32_e32 v53, v53
	v_lshlrev_b32_e32 v45, 16, v111
	v_add_f32_e32 v45, v56, v45
	v_add_co_u32_e32 v60, vcc, s1, v76
	v_add_f32_e32 v53, 1.0, v53
	v_rcp_f32_e32 v53, v53
	v_addc_co_u32_e32 v61, vcc, 0, v77, vcc
	s_mov_b32 s1, 0x2681d000
	v_fma_f32 v49, -v53, v49, v49
	v_mul_f32_e32 v45, v49, v45
	v_bfe_u32 v49, v45, 16, 1
	v_add3_u32 v45, v45, v49, s43
	global_store_short_d16_hi v[60:61], v45, off offset:2048
	v_fmamk_f32 v45, v52, 0xbfb8aa3b, v81
	v_exp_f32_e32 v45, v45
	v_add_f32_e32 v47, 1.0, v47
	v_rcp_f32_e32 v47, v47
	v_exp_f32_e32 v46, v46
	v_add_f32_e32 v45, 1.0, v45
	v_rcp_f32_e32 v45, v45
	v_lshl_add_u64 v[72:73], v[72:73], 0, s[4:5]
	v_add_f32_e32 v46, 1.0, v46
	v_rcp_f32_e32 v46, v46
	v_mul_f32_e32 v45, v83, v45
	v_exp_f32_e32 v45, v45
	s_waitcnt vmcnt(6)
	v_mov_b32_e32 v110, v96
	s_waitcnt vmcnt(4)
	v_mov_b32_e32 v75, v103
	s_waitcnt vmcnt(3)
; #define LAS __attribute__((address_space(3)))
; __device__ __forceinline__ unsigned f2bf(float f) { unsigned u = __builtin_bit_cast(unsigned, f); return (u + 0x7fffu + ((u >> 16) & 1u)) >> 16; }
; __device__ __forceinline__ float frcp(float x) { return __builtin_amdgcn_rcpf(x); }
; template <int MODE, int DIR> __device__ __forceinline__ void lru_dir(const Args& a, int l, int lane, int tok0, int nb, int half, const LAS unsigned char* xt, bf16* hf) {
;     ...
;             if (step + 1 < NST) {
; #pragma unroll
;                 for (int rg = 0; rg < 4; ++rg)
; #pragma unroll
;                     for (int c2 = 0; c2 < 2; ++c2) { yn[c2][rg] = hf[((((t4 + DT) >> 2) * 4 + rg) * 2 + c2) * 64 + lane]; gn[c2][rg] = go[(size_t)(t4 + DT + rg) * ZRW + 16 * c2]; } } }
;         const pg8::bf16x8 a0 = *(const LAS pg8::bf16x8*)(xa + t4 * 128), a1 = *(const LAS pg8::bf16x8*)(xa + t4 * 128 + 64);
;         const pg8::bf16x8 ah = half ? a1 : a0;
;         f32x4 pa[2], px[2], xd[2];
; #pragma unroll
;         for (int c2 = 0; c2 < 2; ++c2) { const f32x4 z4 = (f32x4){0.f, 0.f, 0.f, 0.f};
;             pa[c2] = __builtin_amdgcn_mfma_f32_16x16x32_bf16(a0, wa[c2][0], z4, 0, 0, 0); pa[c2] = __builtin_amdgcn_mfma_f32_16x16x32_bf16(a1, wa[c2][1], pa[c2], 0, 0, 0);
;             px[c2] = __builtin_amdgcn_mfma_f32_16x16x32_bf16(a0, wx[c2][0], z4, 0, 0, 0); px[c2] = __builtin_amdgcn_mfma_f32_16x16x32_bf16(a1, wx[c2][1], px[c2], 0, 0, 0);
;             xd[c2] = __builtin_amdgcn_mfma_f32_16x16x32_bf16(ah, idn[c2], z4, 0, 0, 0); }
; #pragma unroll
;         for (int rr = 0; rr < 4; ++rr) { const int rg = DIR ? 3 - rr : rr;
; #pragma unroll
;             for (int c2 = 0; c2 < 2; ++c2) {
;                 const float r_ = frcp(1.f + __builtin_amdgcn_exp2f(__builtin_fmaf(pa[c2][rg], -1.4426950408889634f, ba[c2]))), i_ = frcp(1.f + __builtin_amdgcn_exp2f(__builtin_fmaf(px[c2][rg], -1.4426950408889634f, bx[c2])));
;                 const float av = __builtin_amdgcn_exp2f(ls8[c2] * r_), mult = fsqrt_(fmaxf(1.f - av * av, 0.f));
;                 h[c2] = av * h[c2] + mult * i_ * xd[c2][rg]; P[c2] *= av;
;                 if (MODE) {
;                     if (DIR == 0) hf[(((t4 >> 2) * 4 + rg) * 2 + c2) * 64 + lane] = (bf16)f2bf(h[c2]);
;                     else yo[(size_t)(t4 + rg) * DM + 16 * c2] = (bf16)f2bf((bf2f(yc[c2][rg]) + h[c2]) * gelu_tanh(bf2f(gc[c2][rg]))); } }
	v_mov_b32_e32 v112, v107
	v_fma_f32 v49, -v45, v45, 1.0
	v_max_f32_e32 v49, 0, v49
	v_sqrt_f32_e32 v49, v49
	v_mul_f32_e32 v52, v45, v74
	v_mov_b32_e32 v111, v220
	v_lshrrev_b32_e32 v113, 16, v221
	v_mul_f32_e32 v48, v48, v49
	v_mov_b32_e32 v49, v74
	v_pk_fma_f32 v[44:45], v[44:45], v[48:49], v[52:53] op_sel_hi:[1,1,0]
	v_lshlrev_b32_e32 v48, 16, v108
	v_mul_f32_e32 v49, v48, v48
	v_mul_f32_e32 v52, 0x40135761, v48
	v_fma_f32 v49, v49, s58, 1.0
	v_mul_f32_e32 v49, v52, v49
	v_exp_f32_e32 v49, v49
	v_lshlrev_b32_e32 v45, 16, v109
	v_add_f32_e32 v45, v44, v45
	v_mov_b32_e32 v53, v56
	v_add_f32_e32 v49, 1.0, v49
	v_rcp_f32_e32 v49, v49
	v_mov_b32_e32 v108, v98
	v_lshrrev_b32_e32 v109, 16, v220
	v_fma_f32 v48, -v49, v48, v48
	v_mul_f32_e32 v45, v48, v45
	v_bfe_u32 v48, v45, 16, 1
	v_add3_u32 v45, v45, v48, s43
	global_store_short_d16_hi v[60:61], v45, off offset:2080
	v_fmamk_f32 v45, v63, 0xbfb8aa3b, v78
	v_exp_f32_e32 v45, v45
	v_fmamk_f32 v48, v59, 0xbfb8aa3b, v79
	v_exp_f32_e32 v48, v48
	v_mov_b32_e32 v61, v44
	v_add_f32_e32 v45, 1.0, v45
	v_rcp_f32_e32 v45, v45
	v_add_f32_e32 v48, 1.0, v48
	v_rcp_f32_e32 v48, v48
	v_mul_f32_e32 v45, v80, v45
	v_exp_f32_e32 v49, v45
	s_nop 0
	v_fma_f32 v45, -v49, v49, 1.0
	v_max_f32_e32 v45, 0, v45
	v_sqrt_f32_e32 v45, v45
	v_mul_f32_e32 v56, v49, v56
	v_mul_f32_e32 v52, v48, v45
	v_mov_b32_e32 v48, v55
	v_pk_fma_f32 v[48:49], v[48:49], v[52:53], v[56:57] op_sel_hi:[1,1,0]
	v_lshlrev_b32_e32 v45, 16, v105
	v_lshlrev_b32_e32 v49, 16, v104
	v_mul_f32_e32 v52, v49, v49
	v_mul_f32_e32 v53, 0x40135761, v49
	v_fma_f32 v52, v52, s58, 1.0
	v_mul_f32_e32 v52, v53, v52
	v_exp_f32_e32 v52, v52
	v_add_f32_e32 v45, v48, v45
	v_mov_b32_e32 v56, v43
	v_mov_b32_e32 v104, v95
	v_add_f32_e32 v52, 1.0, v52
	v_rcp_f32_e32 v52, v52
	v_mov_b32_e32 v105, v219
	v_fma_f32 v49, -v52, v49, v49
	v_mul_f32_e32 v45, v49, v45
	v_bfe_u32 v49, v45, 16, 1
	v_add_co_u32_e32 v52, vcc, s1, v76
	v_add3_u32 v45, v45, v49, s43
	s_nop 0
	v_addc_co_u32_e32 v53, vcc, 0, v77, vcc
	global_store_short_d16_hi v[52:53], v45, off offset:2048
	v_fmamk_f32 v45, v51, 0xbfb8aa3b, v81
	v_exp_f32_e32 v45, v45
	s_mov_b32 s1, 0x2681c000
	v_add_f32_e32 v45, 1.0, v45
	v_rcp_f32_e32 v45, v45
	s_nop 0
	v_mul_f32_e32 v45, v83, v45
	v_exp_f32_e32 v57, v45
	s_nop 0
	v_fma_f32 v45, -v57, v57, 1.0
	v_max_f32_e32 v45, 0, v45
	v_sqrt_f32_e32 v45, v45
	s_nop 0
	v_mul_f32_e32 v60, v47, v45
	v_pk_mul_f32 v[44:45], v[56:57], v[60:61]
	s_nop 0
	v_add_f32_e32 v43, v44, v45
	v_lshlrev_b32_e32 v45, 16, v88
	v_mul_f32_e32 v47, v45, v45
	v_mul_f32_e32 v49, 0x40135761, v45
	v_fma_f32 v47, v47, s58, 1.0
	v_mul_f32_e32 v47, v49, v47
	v_exp_f32_e32 v47, v47
	v_lshlrev_b32_e32 v44, 16, v89
	v_add_f32_e32 v44, v43, v44
	v_mov_b32_e32 v88, v97
	v_add_f32_e32 v47, 1.0, v47
	v_rcp_f32_e32 v47, v47
	v_lshrrev_b32_e32 v89, 16, v219
	v_fma_f32 v45, -v47, v45, v45
	v_lshlrev_b32_e32 v47, 16, v86
	v_mul_f32_e32 v49, v47, v47
	v_mul_f32_e32 v51, 0x40135761, v47
	v_fma_f32 v49, v49, s58, 1.0
	v_mul_f32_e32 v49, v51, v49
	v_exp_f32_e32 v49, v49
	v_mul_f32_e32 v44, v45, v44
	v_bfe_u32 v45, v44, 16, 1
	v_add3_u32 v44, v44, v45, s43
	v_add_f32_e32 v49, 1.0, v49
	v_rcp_f32_e32 v49, v49
	global_store_short_d16_hi v[52:53], v44, off offset:2080
	v_fmamk_f32 v44, v62, 0xbfb8aa3b, v78
	v_exp_f32_e32 v44, v44
	v_fma_f32 v49, -v49, v47, v47
	v_fmamk_f32 v47, v50, 0xbfb8aa3b, v81
	v_exp_f32_e32 v47, v47
	v_add_f32_e32 v44, 1.0, v44
	v_rcp_f32_e32 v44, v44
	v_fmamk_f32 v45, v58, 0xbfb8aa3b, v79
	v_add_f32_e32 v47, 1.0, v47
	v_rcp_f32_e32 v47, v47
	v_mul_f32_e32 v44, v80, v44
	v_exp_f32_e32 v55, v44
	v_exp_f32_e32 v45, v45
	v_mul_f32_e32 v47, v83, v47
	v_exp_f32_e32 v47, v47
	v_fma_f32 v44, -v55, v55, 1.0
	v_add_f32_e32 v45, 1.0, v45
	v_max_f32_e32 v44, 0, v44
	v_fma_f32 v50, -v47, v47, 1.0
	v_rcp_f32_e32 v45, v45
	v_sqrt_f32_e32 v44, v44
	v_max_f32_e32 v50, 0, v50
	v_sqrt_f32_e32 v50, v50
	v_mul_f32_e32 v43, v47, v43
	v_mul_f32_e32 v44, v45, v44
	v_mov_b32_e32 v45, v48
	v_pk_mul_f32 v[44:45], v[54:55], v[44:45]
	v_mul_f32_e32 v46, v46, v50
	v_mul_f32_e32 v47, v42, v46
	v_mov_b32_e32 v46, v44
	v_mov_b32_e32 v42, v45
	v_lshlrev_b32_e32 v45, 16, v84
	v_pk_add_f32 v[68:69], v[46:47], v[42:43]
	v_mul_f32_e32 v46, v45, v45
	v_mul_f32_e32 v47, 0x40135761, v45
	v_fma_f32 v46, v46, s58, 1.0
	v_mul_f32_e32 v46, v47, v46
	v_exp_f32_e32 v46, v46
	v_lshlrev_b32_e32 v48, 16, v87
	v_add_f32_e32 v42, v68, v48
	v_mul_f32_e32 v42, v49, v42
	v_add_f32_e32 v46, 1.0, v46
	v_bfe_u32 v43, v42, 16, 1
	v_rcp_f32_e32 v46, v46
	v_add3_u32 v44, v42, v43, s43
	v_add_co_u32_e32 v42, vcc, s1, v76
	v_fma_f32 v45, -v46, v45, v45
	s_nop 0
	v_addc_co_u32_e32 v43, vcc, 0, v77, vcc
	global_store_short_d16_hi v[42:43], v44, off offset:2048
	v_lshlrev_b32_e32 v44, 16, v85
	v_add_f32_e32 v44, v69, v44
	v_mul_f32_e32 v44, v45, v44
	v_bfe_u32 v45, v44, 16, 1
	v_add3_u32 v44, v44, v45, s43
	v_mov_b32_e32 v86, v91
	v_mov_b32_e32 v84, v92
	v_mov_b32_e32 v87, v218
	v_mov_b32_e32 v76, v221
	v_lshrrev_b32_e32 v85, 16, v218
	v_mov_b32_e32 v74, v69
	global_store_short_d16_hi v[42:43], v44, off offset:2080
	s_cbranch_scc1 .LBB0_657
.LBB0_717:
	s_cmp_eq_u32 s0, 0
	s_cbranch_scc1 .LBB0_716
	v_lshl_add_u64 v[44:45], s[90:91], 0, v[70:71]
	v_add_co_u32_e32 v44, vcc, 0x33001000, v44
	v_lshl_add_u64 v[42:43], s[90:91], 0, v[66:67]
	s_nop 0
	v_addc_co_u32_e32 v45, vcc, 0, v45, vcc
	v_add_co_u32_e32 v46, vcc, 0x1f012000, v42
	v_lshl_add_u64 v[212:213], v[44:45], 0, v[210:211]
	global_load_dwordx4 v[218:221], v[212:213], off offset:2048
	s_nop 0
	v_addc_co_u32_e32 v47, vcc, 0, v43, vcc
	global_load_ushort v91, v[46:47], off offset:1024
	global_load_ushort v92, v[46:47], off offset:1056
	v_add_co_u32_e32 v46, vcc, 0x1f013000, v42
	s_nop 1
	v_addc_co_u32_e32 v47, vcc, 0, v43, vcc
	global_load_ushort v95, v[46:47], off
	global_load_ushort v97, v[46:47], off offset:32
	global_load_ushort v96, v[46:47], off offset:3072
	global_load_ushort v98, v[46:47], off offset:3104
	v_add_co_u32_e32 v42, vcc, 0x1f014000, v42
	s_nop 1
	v_addc_co_u32_e32 v43, vcc, 0, v43, vcc
	global_load_ushort v103, v[42:43], off offset:2048
	global_load_ushort v107, v[42:43], off offset:2080
	s_branch .LBB0_716
